# all four GEMM K-loops: LDS-DMA issue uses saddr form with per-tile precomputed VGPR offsets (removes per-load v_mov + two 64-bit VALU adds)
# speedup vs baseline: 1.0284x; 1.0065x over previous
; #define PG8_STAGE(bufoff, gbase, voff) do { _Pragma("unroll") for (int _i = 0; _i < 2; ++_i) { unsigned vo_ = (voff)[0]; asm volatile("" : "+v"(vo_));   \
;         __builtin_amdgcn_global_load_lds((const unsigned*)((const char*)(gbase) + (size_t)_i * r64step + vo_), (PG8_LAS unsigned*)(lds + (bufoff) + ldsw + _i * 8192), 16, 0, 0); } } while (0)
; #define PG8_SCHED __builtin_amdgcn_sched_barrier(0)
;     __device__ bool next(int i, Unit& u) const { return i == 0 && base.next(round, u); }
; template <class Epi, class Sched, bool ALIGN_EPI = false, bool SP2 = false, bool F8 = false>
; __device__ __forceinline__ void gemm_phase(PG8_LAS unsigned char* lds, const Gemm g, const Sched& S, const Epi& E) {
;     ...
;     for (;;) {
;         const bool has_next = S.next(ui + 1, nxt);
;         const char* nA = has_next ? (const char*)g.A + (size_t)nxt.pm * tstep : cA; const char* nB = has_next ? (const char*)g.Bt + (size_t)nxt.pn * tstep : cB;
;         for (int t = 0; t < nt; t += 2) {
;             const bool last = (t == nt - 2);
;             const char* a1 = cA + (size_t)(t + 1) * kstep;
;             const char* a2 = last ? nA : cA + (size_t)(t + 2) * kstep; const char* b2 = last ? nB : cB + (size_t)(t + 2) * kstep;
;             const char* a3 = a2 + kstep; const char* b3 = b2 + kstep;
;             if (last && has_next) S.a_ready(nxt);
;             if constexpr (Epi::HOOK_T >= 0) { if (t == Epi::HOOK_T) E.mid(acc, cur, wr, wc, fr, fq); }
;             if constexpr (SP2) {
;             PG8_LDB(B0, 0, 0); PG8_LDB(B1, 0, 1); PG8_SCHED; PG8_LDA(At, 0, 0); PG8_STAGE(PG8_SA(1, 1), a1 + hstep, voffA);
;     ...
; #pragma unroll
;         for (int a = 0; a < 2; ++a)
; #pragma unroll
;             for (int b = 0; b < 2; ++b)
; #pragma unroll
;                 for (int m = 0; m < 4; ++m)
; #pragma unroll
;                     for (int n = 0; n < 2; ++n) acc[a][b][m][n] = (f32x4){0.f, 0.f, 0.f, 0.f};
.LBB0_125:
	s_ashr_i32 s31, s30, 31
	s_lshl_b64 s[34:35], s[30:31], 19
	s_add_u32 s34, s82, s34
	s_addc_u32 s35, s83, s35
	s_and_b64 s[36:37], s[0:1], exec
	s_cselect_b32 s5, s35, s41
	s_cselect_b32 s31, s34, s40
	s_ashr_i32 s29, s28, 31
	s_lshl_b64 s[36:37], s[28:29], 19
	s_add_u32 s36, s25, s36
	s_addc_u32 s37, s46, s37
	s_and_b64 s[44:45], s[0:1], exec
	s_cselect_b32 s29, s37, s43
	s_cselect_b32 s61, s36, s42
	s_add_u32 s40, s40, 0x60080
	s_addc_u32 s41, s41, 0
	s_add_u32 s62, s42, 0x100
	v_mov_b32_e32 v8, 0
	s_addc_u32 s63, s43, 0
	s_mov_b32 s64, -2
	v_mov_b32_e32 v9, v8
	v_mov_b32_e32 v10, v8
	v_mov_b32_e32 v11, v8
	v_mov_b32_e32 v12, v8
	v_mov_b32_e32 v13, v8
	v_mov_b32_e32 v14, v8
	v_mov_b32_e32 v15, v8
	v_mov_b32_e32 v24, v8
	v_mov_b32_e32 v25, v8
	v_mov_b32_e32 v26, v8
	v_mov_b32_e32 v27, v8
	v_mov_b32_e32 v28, v8
	v_mov_b32_e32 v29, v8
	v_mov_b32_e32 v30, v8
	v_mov_b32_e32 v31, v8
	v_mov_b32_e32 v40, v8
	v_mov_b32_e32 v41, v8
	v_mov_b32_e32 v42, v8
	v_mov_b32_e32 v43, v8
	v_mov_b32_e32 v44, v8
	v_mov_b32_e32 v45, v8
	v_mov_b32_e32 v46, v8
	v_mov_b32_e32 v47, v8
	v_mov_b32_e32 v56, v8
	v_mov_b32_e32 v57, v8
	v_mov_b32_e32 v58, v8
	v_mov_b32_e32 v59, v8
	v_mov_b32_e32 v60, v8
	v_mov_b32_e32 v61, v8
	v_mov_b32_e32 v62, v8
	v_mov_b32_e32 v63, v8
	v_mov_b32_e32 v4, v8
	v_mov_b32_e32 v5, v8
	v_mov_b32_e32 v6, v8
	v_mov_b32_e32 v7, v8
	v_mov_b32_e32 v0, v8
	v_mov_b32_e32 v1, v8
	v_mov_b32_e32 v2, v8
	v_mov_b32_e32 v3, v8
	v_mov_b32_e32 v16, v8
	v_mov_b32_e32 v17, v8
	v_mov_b32_e32 v18, v8
	v_mov_b32_e32 v19, v8
	v_mov_b32_e32 v20, v8
	v_mov_b32_e32 v21, v8
	v_mov_b32_e32 v22, v8
	v_mov_b32_e32 v23, v8
	v_mov_b32_e32 v32, v8
	v_mov_b32_e32 v33, v8
	v_mov_b32_e32 v34, v8
	v_mov_b32_e32 v35, v8
	v_mov_b32_e32 v36, v8
	v_mov_b32_e32 v37, v8
	v_mov_b32_e32 v38, v8
	v_mov_b32_e32 v39, v8
	v_mov_b32_e32 v48, v8
	v_mov_b32_e32 v49, v8
	v_mov_b32_e32 v50, v8
	v_mov_b32_e32 v51, v8
	v_mov_b32_e32 v52, v8
	v_mov_b32_e32 v53, v8
	v_mov_b32_e32 v54, v8
	v_mov_b32_e32 v55, v8
	v_mov_b32_e32 v72, v8
	v_mov_b32_e32 v73, v8
	v_mov_b32_e32 v74, v8
	v_mov_b32_e32 v75, v8
	v_mov_b32_e32 v76, v8
	v_mov_b32_e32 v77, v8
	v_mov_b32_e32 v78, v8
	v_mov_b32_e32 v79, v8
	v_mov_b32_e32 v88, v8
	v_mov_b32_e32 v89, v8
	v_mov_b32_e32 v90, v8
	v_mov_b32_e32 v91, v8
	v_mov_b32_e32 v100, v8
	v_mov_b32_e32 v101, v8
	v_mov_b32_e32 v102, v8
	v_mov_b32_e32 v103, v8
	v_mov_b32_e32 v120, v8
	v_mov_b32_e32 v121, v8
	v_mov_b32_e32 v122, v8
	v_mov_b32_e32 v123, v8
	v_mov_b32_e32 v124, v8
	v_mov_b32_e32 v125, v8
	v_mov_b32_e32 v126, v8
	v_mov_b32_e32 v127, v8
	v_mov_b32_e32 v136, v8
	v_mov_b32_e32 v137, v8
	v_mov_b32_e32 v138, v8
	v_mov_b32_e32 v139, v8
	v_mov_b32_e32 v140, v8
	v_mov_b32_e32 v141, v8
	v_mov_b32_e32 v142, v8
	v_mov_b32_e32 v143, v8
	v_mov_b32_e32 v64, v8
	v_mov_b32_e32 v65, v8
	v_mov_b32_e32 v66, v8
	v_mov_b32_e32 v67, v8
	v_mov_b32_e32 v68, v8
	v_mov_b32_e32 v69, v8
	v_mov_b32_e32 v70, v8
	v_mov_b32_e32 v71, v8
	v_mov_b32_e32 v80, v8
	v_mov_b32_e32 v81, v8
	v_mov_b32_e32 v82, v8
	v_mov_b32_e32 v83, v8
	v_mov_b32_e32 v84, v8
	v_mov_b32_e32 v85, v8
	v_mov_b32_e32 v86, v8
	v_mov_b32_e32 v87, v8
	v_mov_b32_e32 v112, v8
	v_mov_b32_e32 v113, v8
	v_mov_b32_e32 v114, v8
	v_mov_b32_e32 v115, v8
	v_mov_b32_e32 v116, v8
	v_mov_b32_e32 v117, v8
	v_mov_b32_e32 v118, v8
	v_mov_b32_e32 v119, v8
	v_mov_b32_e32 v128, v8
	v_mov_b32_e32 v129, v8
	v_mov_b32_e32 v130, v8
	v_mov_b32_e32 v131, v8
	v_mov_b32_e32 v132, v8
	v_mov_b32_e32 v133, v8
	v_mov_b32_e32 v134, v8
	v_mov_b32_e32 v135, v8
	v_add_u32_e32 v212, s6, v154
	v_add_u32_e32 v213, s8, v154
	v_add_u32_e32 v214, s10, v154
	v_add_u32_e32 v215, s6, v145
	v_add_u32_e32 v216, s8, v145
	v_add_u32_e32 v217, s10, v145
	v_add_u32_e32 v218, s14, v154
	v_add_u32_e32 v219, s16, v154
	v_add_u32_e32 v220, s18, v154
	v_add_u32_e32 v221, s20, v154
	v_add_u32_e32 v222, s14, v145
	v_add_u32_e32 v223, s16, v145
.LBB0_126:
	ds_read_b128 v[92:95], v158
	ds_read_b128 v[96:99], v158 offset:1024
	ds_read_b128 v[104:107], v158 offset:2048
	ds_read_b128 v[108:111], v158 offset:3072
	ds_read_b128 v[162:165], v159
	ds_read_b128 v[166:169], v159 offset:1024
	ds_read_b128 v[172:175], v159 offset:2048
	ds_read_b128 v[176:179], v159 offset:3072
	s_add_u32 s42, s40, 0xfffa0080
	s_addc_u32 s43, s41, -1
	s_cmp_eq_u32 s64, 12
	s_cselect_b32 s43, s5, s43
	s_cselect_b32 s42, s31, s42
	s_cselect_b32 s45, s29, s63
	s_cselect_b32 s44, s61, s62
	ds_read_b128 v[180:183], v160
	ds_read_b128 v[184:187], v160 offset:1024
	ds_read_b128 v[188:191], v160 offset:2048
	ds_read_b128 v[192:195], v160 offset:3072
	ds_read_b128 v[196:199], v160 offset:4096
	ds_read_b128 v[200:203], v160 offset:5120
	ds_read_b128 v[204:207], v160 offset:6144
	ds_read_b128 v[208:211], v160 offset:7168
	s_add_i32 m0, s39, 0xc000
	s_add_u32 s100, s40, s26
	s_addc_u32 s101, s41, s27
	global_load_lds_dwordx4 v145, s[100:101]
	s_add_i32 m0, s39, 0xe000
	s_nop 0
	global_load_lds_dwordx4 v145, s[40:41]
	s_waitcnt vmcnt(8)
	s_waitcnt lgkmcnt(0)
	s_barrier
; #define PG8_STAGE(bufoff, gbase, voff) do { _Pragma("unroll") for (int _i = 0; _i < 2; ++_i) { unsigned vo_ = (voff)[0]; asm volatile("" : "+v"(vo_));   \
;         __builtin_amdgcn_global_load_lds((const unsigned*)((const char*)(gbase) + (size_t)_i * r64step + vo_), (PG8_LAS unsigned*)(lds + (bufoff) + ldsw + _i * 8192), 16, 0, 0); } } while (0)
; #define PG8_WAIT_V(n) asm volatile("s_waitcnt vmcnt(" #n ")" ::: "memory")
; #define PG8_WAIT_L(n) asm volatile("s_waitcnt lgkmcnt(" #n ")" ::: "memory")
; #define PG8_BAR __builtin_amdgcn_s_barrier()
; #define PG8_SCHED __builtin_amdgcn_sched_barrier(0)
; template <class Epi, class Sched, bool ALIGN_EPI = false, bool SP2 = false, bool F8 = false>
; __device__ __forceinline__ void gemm_phase(PG8_LAS unsigned char* lds, const Gemm g, const Sched& S, const Epi& E) {
;     ...
;             PG8_LDB(B0, 0, 0); PG8_LDB(B1, 0, 1); PG8_SCHED; PG8_LDA(At, 0, 0); PG8_STAGE(PG8_SA(1, 1), a1 + hstep, voffA);
;             PG8_WAIT_V(8); PG8_WAIT_L(0); PG8_BAR; PG8_MMA(0, 0, At, B0); PG8_MMA(0, 1, At, B1); PG8_BAR; PG8_SCHED;
;             PG8_LDA(At, 0, 1); PG8_STAGE(PG8_SB(0, 0), b2, voffB); PG8_STAGE(PG8_SB(0, 1), b2 + hstep, voffB); PG8_STAGE(PG8_SA(0, 0), a2, voffA);
;             PG8_WAIT_V(8); PG8_WAIT_L(0); PG8_BAR; PG8_MMA(1, 0, At, B0); PG8_MMA(1, 1, At, B1); PG8_BAR; PG8_SCHED;
	s_setprio 1
	s_waitcnt lgkmcnt(0)
	v_mfma_f32_16x16x32_bf16 v[132:135], v[92:95], v[180:183], v[132:135]
	v_mfma_f32_16x16x32_bf16 v[128:131], v[104:107], v[180:183], v[128:131]
	v_mfma_f32_16x16x32_bf16 v[116:119], v[92:95], v[188:191], v[116:119]
	v_mfma_f32_16x16x32_bf16 v[112:115], v[104:107], v[188:191], v[112:115]
	v_mfma_f32_16x16x32_bf16 v[84:87], v[92:95], v[196:199], v[84:87]
	v_mfma_f32_16x16x32_bf16 v[80:83], v[104:107], v[196:199], v[80:83]
	v_mfma_f32_16x16x32_bf16 v[68:71], v[92:95], v[204:207], v[68:71]
	v_mfma_f32_16x16x32_bf16 v[64:67], v[104:107], v[204:207], v[64:67]
	v_mfma_f32_16x16x32_bf16 v[132:135], v[96:99], v[184:187], v[132:135]
	v_mfma_f32_16x16x32_bf16 v[128:131], v[108:111], v[184:187], v[128:131]
	v_mfma_f32_16x16x32_bf16 v[116:119], v[96:99], v[192:195], v[116:119]
	v_mfma_f32_16x16x32_bf16 v[112:115], v[108:111], v[192:195], v[112:115]
	v_mfma_f32_16x16x32_bf16 v[84:87], v[96:99], v[200:203], v[84:87]
	v_mfma_f32_16x16x32_bf16 v[80:83], v[108:111], v[200:203], v[80:83]
	v_mfma_f32_16x16x32_bf16 v[68:71], v[96:99], v[208:211], v[68:71]
	v_mfma_f32_16x16x32_bf16 v[64:67], v[108:111], v[208:211], v[64:67]
	s_setprio 0
	s_setprio 1
	v_mfma_f32_16x16x32_bf16 v[140:143], v[162:165], v[180:183], v[140:143]
	v_mfma_f32_16x16x32_bf16 v[136:139], v[172:175], v[180:183], v[136:139]
	v_mfma_f32_16x16x32_bf16 v[124:127], v[162:165], v[188:191], v[124:127]
	v_mfma_f32_16x16x32_bf16 v[120:123], v[172:175], v[188:191], v[120:123]
	v_mfma_f32_16x16x32_bf16 v[100:103], v[162:165], v[196:199], v[100:103]
	v_mfma_f32_16x16x32_bf16 v[88:91], v[172:175], v[196:199], v[88:91]
	v_mfma_f32_16x16x32_bf16 v[76:79], v[162:165], v[204:207], v[76:79]
	v_mfma_f32_16x16x32_bf16 v[72:75], v[172:175], v[204:207], v[72:75]
	v_mfma_f32_16x16x32_bf16 v[140:143], v[166:169], v[184:187], v[140:143]
	v_mfma_f32_16x16x32_bf16 v[136:139], v[176:179], v[184:187], v[136:139]
	v_mfma_f32_16x16x32_bf16 v[124:127], v[166:169], v[192:195], v[124:127]
	v_mfma_f32_16x16x32_bf16 v[120:123], v[176:179], v[192:195], v[120:123]
	v_mfma_f32_16x16x32_bf16 v[100:103], v[166:169], v[200:203], v[100:103]
	v_mfma_f32_16x16x32_bf16 v[88:91], v[176:179], v[200:203], v[88:91]
	v_mfma_f32_16x16x32_bf16 v[76:79], v[166:169], v[208:211], v[76:79]
	v_mfma_f32_16x16x32_bf16 v[72:75], v[176:179], v[208:211], v[72:75]
	s_setprio 0
	s_barrier
	s_add_i32 s65, s57, s47
	ds_read_b128 v[180:183], v160 offset:16384
	ds_read_b128 v[184:187], v160 offset:17408
	ds_read_b128 v[188:191], v160 offset:18432
	ds_read_b128 v[192:195], v160 offset:19456
	ds_read_b128 v[196:199], v160 offset:20480
	ds_read_b128 v[200:203], v160 offset:21504
	ds_read_b128 v[204:207], v160 offset:22528
	ds_read_b128 v[208:211], v160 offset:23552
	s_mov_b32 m0, s65
	s_nop 0
	global_load_lds_dwordx4 v154, s[44:45]
	s_add_i32 m0, s65, 0x2000
	s_nop 0
	global_load_lds_dwordx4 v212, s[44:45]
	s_add_i32 s65, s58, s47
	s_mov_b32 m0, s65
	s_nop 0
	global_load_lds_dwordx4 v213, s[44:45]
	s_add_i32 m0, s65, 0x2000
	s_nop 0
	global_load_lds_dwordx4 v214, s[44:45]
	s_mov_b32 m0, s39
	s_nop 0
	global_load_lds_dwordx4 v145, s[42:43]
	s_mov_b32 m0, s48
	s_nop 0
	global_load_lds_dwordx4 v215, s[42:43]
	s_waitcnt vmcnt(8)
	s_waitcnt lgkmcnt(0)
	s_barrier
	s_setprio 1
	s_waitcnt lgkmcnt(0)
	v_mfma_f32_16x16x32_bf16 v[52:55], v[92:95], v[180:183], v[52:55]
	v_mfma_f32_16x16x32_bf16 v[48:51], v[104:107], v[180:183], v[48:51]
	v_mfma_f32_16x16x32_bf16 v[36:39], v[92:95], v[188:191], v[36:39]
	v_mfma_f32_16x16x32_bf16 v[32:35], v[104:107], v[188:191], v[32:35]
	v_mfma_f32_16x16x32_bf16 v[20:23], v[92:95], v[196:199], v[20:23]
	v_mfma_f32_16x16x32_bf16 v[16:19], v[104:107], v[196:199], v[16:19]
	v_mfma_f32_16x16x32_bf16 v[0:3], v[92:95], v[204:207], v[0:3]
	v_mfma_f32_16x16x32_bf16 v[4:7], v[104:107], v[204:207], v[4:7]
	v_mfma_f32_16x16x32_bf16 v[52:55], v[96:99], v[184:187], v[52:55]
	v_mfma_f32_16x16x32_bf16 v[48:51], v[108:111], v[184:187], v[48:51]
	v_mfma_f32_16x16x32_bf16 v[36:39], v[96:99], v[192:195], v[36:39]
	v_mfma_f32_16x16x32_bf16 v[32:35], v[108:111], v[192:195], v[32:35]
	v_mfma_f32_16x16x32_bf16 v[20:23], v[96:99], v[200:203], v[20:23]
	v_mfma_f32_16x16x32_bf16 v[16:19], v[108:111], v[200:203], v[16:19]
	v_mfma_f32_16x16x32_bf16 v[0:3], v[96:99], v[208:211], v[0:3]
	v_mfma_f32_16x16x32_bf16 v[4:7], v[108:111], v[208:211], v[4:7]
	s_setprio 0
	s_setprio 1
	v_mfma_f32_16x16x32_bf16 v[60:63], v[162:165], v[180:183], v[60:63]
	v_mfma_f32_16x16x32_bf16 v[56:59], v[172:175], v[180:183], v[56:59]
	v_mfma_f32_16x16x32_bf16 v[44:47], v[162:165], v[188:191], v[44:47]
	v_mfma_f32_16x16x32_bf16 v[40:43], v[172:175], v[188:191], v[40:43]
	v_mfma_f32_16x16x32_bf16 v[28:31], v[162:165], v[196:199], v[28:31]
	v_mfma_f32_16x16x32_bf16 v[24:27], v[172:175], v[196:199], v[24:27]
	v_mfma_f32_16x16x32_bf16 v[12:15], v[162:165], v[204:207], v[12:15]
	v_mfma_f32_16x16x32_bf16 v[8:11], v[172:175], v[204:207], v[8:11]
	v_mfma_f32_16x16x32_bf16 v[60:63], v[166:169], v[184:187], v[60:63]
	v_mfma_f32_16x16x32_bf16 v[56:59], v[176:179], v[184:187], v[56:59]
	v_mfma_f32_16x16x32_bf16 v[44:47], v[166:169], v[192:195], v[44:47]
	v_mfma_f32_16x16x32_bf16 v[40:43], v[176:179], v[192:195], v[40:43]
	v_mfma_f32_16x16x32_bf16 v[28:31], v[166:169], v[200:203], v[28:31]
	v_mfma_f32_16x16x32_bf16 v[24:27], v[176:179], v[200:203], v[24:27]
	v_mfma_f32_16x16x32_bf16 v[12:15], v[166:169], v[208:211], v[12:15]
	v_mfma_f32_16x16x32_bf16 v[8:11], v[176:179], v[208:211], v[8:11]
	s_setprio 0
	s_barrier
; #define PG8_STAGE(bufoff, gbase, voff) do { _Pragma("unroll") for (int _i = 0; _i < 2; ++_i) { unsigned vo_ = (voff)[0]; asm volatile("" : "+v"(vo_));   \
;         __builtin_amdgcn_global_load_lds((const unsigned*)((const char*)(gbase) + (size_t)_i * r64step + vo_), (PG8_LAS unsigned*)(lds + (bufoff) + ldsw + _i * 8192), 16, 0, 0); } } while (0)
; #define PG8_WAIT_V(n) asm volatile("s_waitcnt vmcnt(" #n ")" ::: "memory")
; #define PG8_WAIT_L(n) asm volatile("s_waitcnt lgkmcnt(" #n ")" ::: "memory")
; #define PG8_BAR __builtin_amdgcn_s_barrier()
; #define PG8_SCHED __builtin_amdgcn_sched_barrier(0)
; template <class Epi, class Sched, bool ALIGN_EPI = false, bool SP2 = false, bool F8 = false>
; __device__ __forceinline__ void gemm_phase(PG8_LAS unsigned char* lds, const Gemm g, const Sched& S, const Epi& E) {
;     ...
;             PG8_LDB(B0, 1, 0); PG8_LDB(B1, 1, 1); PG8_SCHED; PG8_LDA(At, 1, 0); PG8_STAGE(PG8_SA(0, 1), a2 + hstep, voffA);
;             PG8_WAIT_V(8); PG8_WAIT_L(0); PG8_BAR; PG8_MMA(0, 0, At, B0); PG8_MMA(0, 1, At, B1); PG8_BAR; PG8_SCHED;
;             PG8_LDA(At, 1, 1); PG8_STAGE(PG8_SB(1, 0), b3, voffB); PG8_STAGE(PG8_SB(1, 1), b3 + hstep, voffB); PG8_STAGE(PG8_SA(1, 0), a3, voffA);
;             PG8_WAIT_V(8); PG8_WAIT_L(0); PG8_BAR; PG8_MMA(1, 0, At, B0); PG8_MMA(1, 1, At, B1); PG8_BAR; PG8_SCHED;
	s_add_i32 s65, 0, 0x18000
	s_add_i32 s66, 0, 0x1c000
	v_add_u32_e32 v108, s65, v156
	v_add_u32_e32 v146, s66, v156
	ds_read_b128 v[92:95], v108
	ds_read_b128 v[96:99], v108 offset:1024
	ds_read_b128 v[104:107], v108 offset:2048
	ds_read_b128 v[108:111], v108 offset:3072
	ds_read_b128 v[162:165], v146
	ds_read_b128 v[166:169], v146 offset:1024
	ds_read_b128 v[172:175], v146 offset:2048
	ds_read_b128 v[176:179], v146 offset:3072
	ds_read_b128 v[180:183], v160 offset:32768
	ds_read_b128 v[184:187], v160 offset:33792
	ds_read_b128 v[188:191], v160 offset:34816
	ds_read_b128 v[192:195], v160 offset:35840
	ds_read_b128 v[196:199], v160 offset:36864
	ds_read_b128 v[200:203], v160 offset:37888
	ds_read_b128 v[204:207], v160 offset:38912
	ds_read_b128 v[208:211], v160 offset:39936
	s_mov_b32 m0, s49
	s_nop 0
	global_load_lds_dwordx4 v216, s[42:43]
	s_mov_b32 m0, s50
	s_nop 0
	global_load_lds_dwordx4 v217, s[42:43]
	s_waitcnt vmcnt(8)
	s_waitcnt lgkmcnt(0)
	s_barrier
	s_setprio 1
	s_waitcnt lgkmcnt(0)
	v_mfma_f32_16x16x32_bf16 v[132:135], v[92:95], v[180:183], v[132:135]
	v_mfma_f32_16x16x32_bf16 v[128:131], v[104:107], v[180:183], v[128:131]
	v_mfma_f32_16x16x32_bf16 v[116:119], v[92:95], v[188:191], v[116:119]
	v_mfma_f32_16x16x32_bf16 v[112:115], v[104:107], v[188:191], v[112:115]
	v_mfma_f32_16x16x32_bf16 v[84:87], v[92:95], v[196:199], v[84:87]
	v_mfma_f32_16x16x32_bf16 v[80:83], v[104:107], v[196:199], v[80:83]
	v_mfma_f32_16x16x32_bf16 v[68:71], v[92:95], v[204:207], v[68:71]
	v_mfma_f32_16x16x32_bf16 v[64:67], v[104:107], v[204:207], v[64:67]
	v_mfma_f32_16x16x32_bf16 v[132:135], v[96:99], v[184:187], v[132:135]
	v_mfma_f32_16x16x32_bf16 v[128:131], v[108:111], v[184:187], v[128:131]
	v_mfma_f32_16x16x32_bf16 v[116:119], v[96:99], v[192:195], v[116:119]
	v_mfma_f32_16x16x32_bf16 v[112:115], v[108:111], v[192:195], v[112:115]
	v_mfma_f32_16x16x32_bf16 v[84:87], v[96:99], v[200:203], v[84:87]
	v_mfma_f32_16x16x32_bf16 v[80:83], v[108:111], v[200:203], v[80:83]
	v_mfma_f32_16x16x32_bf16 v[68:71], v[96:99], v[208:211], v[68:71]
	v_mfma_f32_16x16x32_bf16 v[64:67], v[108:111], v[208:211], v[64:67]
	s_setprio 0
	s_setprio 1
	v_mfma_f32_16x16x32_bf16 v[140:143], v[162:165], v[180:183], v[140:143]
	v_mfma_f32_16x16x32_bf16 v[136:139], v[172:175], v[180:183], v[136:139]
	v_mfma_f32_16x16x32_bf16 v[124:127], v[162:165], v[188:191], v[124:127]
	v_mfma_f32_16x16x32_bf16 v[120:123], v[172:175], v[188:191], v[120:123]
	v_mfma_f32_16x16x32_bf16 v[100:103], v[162:165], v[196:199], v[100:103]
	v_mfma_f32_16x16x32_bf16 v[88:91], v[172:175], v[196:199], v[88:91]
	v_mfma_f32_16x16x32_bf16 v[76:79], v[162:165], v[204:207], v[76:79]
	v_mfma_f32_16x16x32_bf16 v[72:75], v[172:175], v[204:207], v[72:75]
	v_mfma_f32_16x16x32_bf16 v[140:143], v[166:169], v[184:187], v[140:143]
	v_mfma_f32_16x16x32_bf16 v[136:139], v[176:179], v[184:187], v[136:139]
	v_mfma_f32_16x16x32_bf16 v[124:127], v[166:169], v[192:195], v[124:127]
	v_mfma_f32_16x16x32_bf16 v[120:123], v[176:179], v[192:195], v[120:123]
	v_mfma_f32_16x16x32_bf16 v[100:103], v[166:169], v[200:203], v[100:103]
	v_mfma_f32_16x16x32_bf16 v[88:91], v[176:179], v[200:203], v[88:91]
	v_mfma_f32_16x16x32_bf16 v[76:79], v[166:169], v[208:211], v[76:79]
	v_mfma_f32_16x16x32_bf16 v[72:75], v[176:179], v[208:211], v[72:75]
	s_setprio 0
	s_barrier
	ds_read_b128 v[180:183], v160 offset:49152
	ds_read_b128 v[184:187], v160 offset:50176
	ds_read_b128 v[188:191], v160 offset:51200
	ds_read_b128 v[192:195], v160 offset:52224
	ds_read_b128 v[196:199], v160 offset:53248
	ds_read_b128 v[200:203], v160 offset:54272
	ds_read_b128 v[204:207], v160 offset:55296
	ds_read_b128 v[208:211], v160 offset:56320
	s_add_i32 s65, s65, s47
	s_mov_b32 m0, s65
	s_nop 0
	global_load_lds_dwordx4 v218, s[44:45]
	s_add_i32 m0, s65, 0x2000
	s_nop 0
	global_load_lds_dwordx4 v219, s[44:45]
	s_add_i32 s65, s66, s47
	s_mov_b32 m0, s65
	s_nop 0
	global_load_lds_dwordx4 v220, s[44:45]
	s_add_i32 m0, s65, 0x2000
	s_nop 0
	global_load_lds_dwordx4 v221, s[44:45]
	s_mov_b32 m0, s52
	s_nop 0
	global_load_lds_dwordx4 v222, s[42:43]
	s_mov_b32 m0, s53
	s_nop 0
	global_load_lds_dwordx4 v223, s[42:43]
	s_waitcnt vmcnt(8)
	s_waitcnt lgkmcnt(0)
	s_barrier
	s_setprio 1
	s_waitcnt lgkmcnt(0)
	v_mfma_f32_16x16x32_bf16 v[52:55], v[92:95], v[180:183], v[52:55]
	v_mfma_f32_16x16x32_bf16 v[48:51], v[104:107], v[180:183], v[48:51]
	v_mfma_f32_16x16x32_bf16 v[36:39], v[92:95], v[188:191], v[36:39]
	v_mfma_f32_16x16x32_bf16 v[32:35], v[104:107], v[188:191], v[32:35]
	v_mfma_f32_16x16x32_bf16 v[20:23], v[92:95], v[196:199], v[20:23]
	v_mfma_f32_16x16x32_bf16 v[16:19], v[104:107], v[196:199], v[16:19]
	v_mfma_f32_16x16x32_bf16 v[0:3], v[92:95], v[204:207], v[0:3]
	v_mfma_f32_16x16x32_bf16 v[4:7], v[104:107], v[204:207], v[4:7]
	v_mfma_f32_16x16x32_bf16 v[52:55], v[96:99], v[184:187], v[52:55]
	v_mfma_f32_16x16x32_bf16 v[48:51], v[108:111], v[184:187], v[48:51]
	v_mfma_f32_16x16x32_bf16 v[36:39], v[96:99], v[192:195], v[36:39]
	v_mfma_f32_16x16x32_bf16 v[32:35], v[108:111], v[192:195], v[32:35]
	v_mfma_f32_16x16x32_bf16 v[20:23], v[96:99], v[200:203], v[20:23]
	v_mfma_f32_16x16x32_bf16 v[16:19], v[108:111], v[200:203], v[16:19]
	v_mfma_f32_16x16x32_bf16 v[0:3], v[96:99], v[208:211], v[0:3]
	v_mfma_f32_16x16x32_bf16 v[4:7], v[108:111], v[208:211], v[4:7]
	s_setprio 0
	s_setprio 1
	v_mfma_f32_16x16x32_bf16 v[60:63], v[162:165], v[180:183], v[60:63]
	v_mfma_f32_16x16x32_bf16 v[56:59], v[172:175], v[180:183], v[56:59]
	v_mfma_f32_16x16x32_bf16 v[44:47], v[162:165], v[188:191], v[44:47]
	v_mfma_f32_16x16x32_bf16 v[40:43], v[172:175], v[188:191], v[40:43]
	v_mfma_f32_16x16x32_bf16 v[28:31], v[162:165], v[196:199], v[28:31]
	v_mfma_f32_16x16x32_bf16 v[24:27], v[172:175], v[196:199], v[24:27]
	v_mfma_f32_16x16x32_bf16 v[12:15], v[162:165], v[204:207], v[12:15]
	v_mfma_f32_16x16x32_bf16 v[8:11], v[172:175], v[204:207], v[8:11]
	v_mfma_f32_16x16x32_bf16 v[60:63], v[166:169], v[184:187], v[60:63]
	v_mfma_f32_16x16x32_bf16 v[56:59], v[176:179], v[184:187], v[56:59]
	v_mfma_f32_16x16x32_bf16 v[44:47], v[166:169], v[192:195], v[44:47]
	v_mfma_f32_16x16x32_bf16 v[40:43], v[176:179], v[192:195], v[40:43]
	v_mfma_f32_16x16x32_bf16 v[28:31], v[166:169], v[200:203], v[28:31]
	v_mfma_f32_16x16x32_bf16 v[24:27], v[176:179], v[200:203], v[24:27]
	v_mfma_f32_16x16x32_bf16 v[12:15], v[166:169], v[208:211], v[12:15]
	v_mfma_f32_16x16x32_bf16 v[8:11], v[176:179], v[208:211], v[8:11]
	s_setprio 0
	s_barrier
	s_add_i32 s64, s64, 2
	s_add_u32 s40, s40, 0x100
	s_addc_u32 s41, s41, 0
	s_add_u32 s62, s62, 0x100
	s_addc_u32 s63, s63, 0
	s_cmp_gt_u32 s64, 13
	s_cbranch_scc0 .LBB0_126
	s_and_b64 vcc, exec, s[22:23]
	s_cbranch_vccz .LBB0_129
	s_barrier

;     __device__ bool next(int i, Unit& u) const { return i == 0 && base.next(round, u); }
; template <class Epi, class Sched, bool ALIGN_EPI = false, bool SP2 = false, bool F8 = false>
; __device__ __forceinline__ void gemm_phase(PG8_LAS unsigned char* lds, const Gemm g, const Sched& S, const Epi& E) {
;     ...
;     for (;;) {
;         const bool has_next = S.next(ui + 1, nxt);
;         const char* nA = has_next ? (const char*)g.A + (size_t)nxt.pm * tstep : cA; const char* nB = has_next ? (const char*)g.Bt + (size_t)nxt.pn * tstep : cB;
;         for (int t = 0; t < nt; t += 2) {
;             const bool last = (t == nt - 2);
;             const char* a1 = cA + (size_t)(t + 1) * kstep;
;             const char* a2 = last ? nA : cA + (size_t)(t + 2) * kstep; const char* b2 = last ? nB : cB + (size_t)(t + 2) * kstep;
;     ...
; #pragma unroll
;         for (int a = 0; a < 2; ++a)
; #pragma unroll
;             for (int b = 0; b < 2; ++b)
; #pragma unroll
;                 for (int m = 0; m < 4; ++m)
; #pragma unroll
;                     for (int n = 0; n < 2; ++n) acc[a][b][m][n] = (f32x4){0.f, 0.f, 0.f, 0.f};
.LBB0_177:
	v_mov_b32_e32 v123, 0
	s_andn2_b64 vcc, exec, s[16:17]
	v_mov_b32_e32 v122, v123
	v_mov_b32_e32 v121, v123
	v_mov_b32_e32 v120, v123
	v_mov_b32_e32 v127, v123
	v_mov_b32_e32 v126, v123
	v_mov_b32_e32 v125, v123
	v_mov_b32_e32 v124, v123
	v_mov_b32_e32 v111, v123
	v_mov_b32_e32 v110, v123
	v_mov_b32_e32 v109, v123
	v_mov_b32_e32 v108, v123
	v_mov_b32_e32 v107, v123
	v_mov_b32_e32 v106, v123
	v_mov_b32_e32 v105, v123
	v_mov_b32_e32 v104, v123
	v_mov_b32_e32 v95, v123
	v_mov_b32_e32 v94, v123
	v_mov_b32_e32 v93, v123
	v_mov_b32_e32 v92, v123
	v_mov_b32_e32 v91, v123
	v_mov_b32_e32 v90, v123
	v_mov_b32_e32 v89, v123
	v_mov_b32_e32 v88, v123
	v_mov_b32_e32 v79, v123
	v_mov_b32_e32 v78, v123
	v_mov_b32_e32 v77, v123
	v_mov_b32_e32 v76, v123
	v_mov_b32_e32 v75, v123
	v_mov_b32_e32 v74, v123
	v_mov_b32_e32 v73, v123
	v_mov_b32_e32 v72, v123
	v_mov_b32_e32 v119, v123
	v_mov_b32_e32 v118, v123
	v_mov_b32_e32 v117, v123
	v_mov_b32_e32 v116, v123
	v_mov_b32_e32 v115, v123
	v_mov_b32_e32 v114, v123
	v_mov_b32_e32 v113, v123
	v_mov_b32_e32 v112, v123
	v_mov_b32_e32 v103, v123
	v_mov_b32_e32 v102, v123
	v_mov_b32_e32 v101, v123
	v_mov_b32_e32 v100, v123
	v_mov_b32_e32 v99, v123
	v_mov_b32_e32 v98, v123
	v_mov_b32_e32 v97, v123
	v_mov_b32_e32 v96, v123
	v_mov_b32_e32 v87, v123
	v_mov_b32_e32 v86, v123
	v_mov_b32_e32 v85, v123
	v_mov_b32_e32 v84, v123
	v_mov_b32_e32 v83, v123
	v_mov_b32_e32 v82, v123
	v_mov_b32_e32 v81, v123
	v_mov_b32_e32 v80, v123
	v_mov_b32_e32 v71, v123
	v_mov_b32_e32 v70, v123
	v_mov_b32_e32 v69, v123
	v_mov_b32_e32 v68, v123
	v_mov_b32_e32 v67, v123
	v_mov_b32_e32 v66, v123
	v_mov_b32_e32 v65, v123
	v_mov_b32_e32 v64, v123
	v_mov_b32_e32 v63, v123
	v_mov_b32_e32 v62, v123
	v_mov_b32_e32 v61, v123
	v_mov_b32_e32 v60, v123
	v_mov_b32_e32 v59, v123
	v_mov_b32_e32 v58, v123
	v_mov_b32_e32 v57, v123
	v_mov_b32_e32 v56, v123
	v_mov_b32_e32 v47, v123
	v_mov_b32_e32 v46, v123
	v_mov_b32_e32 v45, v123
	v_mov_b32_e32 v44, v123
	v_mov_b32_e32 v43, v123
	v_mov_b32_e32 v42, v123
	v_mov_b32_e32 v41, v123
	v_mov_b32_e32 v40, v123
	v_mov_b32_e32 v31, v123
	v_mov_b32_e32 v30, v123
	v_mov_b32_e32 v29, v123
	v_mov_b32_e32 v28, v123
	v_mov_b32_e32 v27, v123
	v_mov_b32_e32 v26, v123
	v_mov_b32_e32 v25, v123
	v_mov_b32_e32 v24, v123
	v_mov_b32_e32 v15, v123
	v_mov_b32_e32 v14, v123
	v_mov_b32_e32 v13, v123
	v_mov_b32_e32 v12, v123
	v_mov_b32_e32 v11, v123
	v_mov_b32_e32 v10, v123
	v_mov_b32_e32 v9, v123
	v_mov_b32_e32 v8, v123
	v_mov_b32_e32 v55, v123
	v_mov_b32_e32 v54, v123
	v_mov_b32_e32 v53, v123
	v_mov_b32_e32 v52, v123
	v_mov_b32_e32 v51, v123
	v_mov_b32_e32 v50, v123
	v_mov_b32_e32 v49, v123
	v_mov_b32_e32 v48, v123
	v_mov_b32_e32 v39, v123
	v_mov_b32_e32 v38, v123
	v_mov_b32_e32 v37, v123
	v_mov_b32_e32 v36, v123
	v_mov_b32_e32 v35, v123
	v_mov_b32_e32 v34, v123
	v_mov_b32_e32 v33, v123
	v_mov_b32_e32 v32, v123
	v_mov_b32_e32 v23, v123
	v_mov_b32_e32 v22, v123
	v_mov_b32_e32 v21, v123
	v_mov_b32_e32 v20, v123
	v_mov_b32_e32 v19, v123
	v_mov_b32_e32 v18, v123
	v_mov_b32_e32 v17, v123
	v_mov_b32_e32 v16, v123
	v_mov_b32_e32 v7, v123
	v_mov_b32_e32 v6, v123
	v_mov_b32_e32 v5, v123
	v_mov_b32_e32 v4, v123
	v_mov_b32_e32 v3, v123
	v_mov_b32_e32 v2, v123
	v_mov_b32_e32 v1, v123
	v_mov_b32_e32 v0, v123
	s_cbranch_vccnz .LBB0_181
	s_add_u32 s72, s34, 0x80
	s_addc_u32 s73, s35, 0
	s_add_u32 s74, s30, 0x100
	v_mov_b32_e32 v0, 0
	s_mov_b64 vcc, s[82:83]
	s_addc_u32 s75, s31, 0
	s_mov_b32 s30, 0
	v_mov_b32_e32 v1, v0
	v_mov_b32_e32 v2, v0
	v_mov_b32_e32 v3, v0
	v_mov_b32_e32 v4, v0
	v_mov_b32_e32 v5, v0
	v_mov_b32_e32 v6, v0
	v_mov_b32_e32 v7, v0
	v_mov_b32_e32 v16, v0
	v_mov_b32_e32 v17, v0
	v_mov_b32_e32 v18, v0
	v_mov_b32_e32 v19, v0
	v_mov_b32_e32 v20, v0
	v_mov_b32_e32 v21, v0
	v_mov_b32_e32 v22, v0
	v_mov_b32_e32 v23, v0
	v_mov_b32_e32 v32, v0
	v_mov_b32_e32 v33, v0
	v_mov_b32_e32 v34, v0
	v_mov_b32_e32 v35, v0
	v_mov_b32_e32 v36, v0
	v_mov_b32_e32 v37, v0
	v_mov_b32_e32 v38, v0
	v_mov_b32_e32 v39, v0
	v_mov_b32_e32 v48, v0
	v_mov_b32_e32 v49, v0
	v_mov_b32_e32 v50, v0
	v_mov_b32_e32 v51, v0
	v_mov_b32_e32 v52, v0
	v_mov_b32_e32 v53, v0
	v_mov_b32_e32 v54, v0
	v_mov_b32_e32 v55, v0
	v_mov_b32_e32 v8, v0
	v_mov_b32_e32 v9, v0
	v_mov_b32_e32 v10, v0
	v_mov_b32_e32 v11, v0
	v_mov_b32_e32 v12, v0
	v_mov_b32_e32 v13, v0
	v_mov_b32_e32 v14, v0
	v_mov_b32_e32 v15, v0
	v_mov_b32_e32 v24, v0
	v_mov_b32_e32 v25, v0
	v_mov_b32_e32 v26, v0
	v_mov_b32_e32 v27, v0
	v_mov_b32_e32 v28, v0
	v_mov_b32_e32 v29, v0
	v_mov_b32_e32 v30, v0
	v_mov_b32_e32 v31, v0
	v_mov_b32_e32 v40, v0
	v_mov_b32_e32 v41, v0
	v_mov_b32_e32 v42, v0
	v_mov_b32_e32 v43, v0
	v_mov_b32_e32 v44, v0
	v_mov_b32_e32 v45, v0
	v_mov_b32_e32 v46, v0
	v_mov_b32_e32 v47, v0
	v_mov_b32_e32 v56, v0
	v_mov_b32_e32 v57, v0
	v_mov_b32_e32 v58, v0
	v_mov_b32_e32 v59, v0
	v_mov_b32_e32 v60, v0
	v_mov_b32_e32 v61, v0
	v_mov_b32_e32 v62, v0
	v_mov_b32_e32 v63, v0
	v_mov_b32_e32 v64, v0
	v_mov_b32_e32 v65, v0
	v_mov_b32_e32 v66, v0
	v_mov_b32_e32 v67, v0
	v_mov_b32_e32 v68, v0
	v_mov_b32_e32 v69, v0
	v_mov_b32_e32 v70, v0
	v_mov_b32_e32 v71, v0
	v_mov_b32_e32 v80, v0
	v_mov_b32_e32 v81, v0
	v_mov_b32_e32 v82, v0
	v_mov_b32_e32 v83, v0
	v_mov_b32_e32 v84, v0
	v_mov_b32_e32 v85, v0
	v_mov_b32_e32 v86, v0
	v_mov_b32_e32 v87, v0
	v_mov_b32_e32 v96, v0
	v_mov_b32_e32 v97, v0
	v_mov_b32_e32 v98, v0
	v_mov_b32_e32 v99, v0
	v_mov_b32_e32 v100, v0
	v_mov_b32_e32 v101, v0
	v_mov_b32_e32 v102, v0
	v_mov_b32_e32 v103, v0
	v_mov_b32_e32 v112, v0
	v_mov_b32_e32 v113, v0
	v_mov_b32_e32 v114, v0
	v_mov_b32_e32 v115, v0
	v_mov_b32_e32 v116, v0
	v_mov_b32_e32 v117, v0
	v_mov_b32_e32 v118, v0
	v_mov_b32_e32 v119, v0
	v_mov_b32_e32 v72, v0
	v_mov_b32_e32 v73, v0
	v_mov_b32_e32 v74, v0
	v_mov_b32_e32 v75, v0
	v_mov_b32_e32 v76, v0
	v_mov_b32_e32 v77, v0
	v_mov_b32_e32 v78, v0
	v_mov_b32_e32 v79, v0
	v_mov_b32_e32 v88, v0
	v_mov_b32_e32 v89, v0
	v_mov_b32_e32 v90, v0
	v_mov_b32_e32 v91, v0
	v_mov_b32_e32 v92, v0
	v_mov_b32_e32 v93, v0
	v_mov_b32_e32 v94, v0
	v_mov_b32_e32 v95, v0
	v_mov_b32_e32 v104, v0
	v_mov_b32_e32 v105, v0
	v_mov_b32_e32 v106, v0
	v_mov_b32_e32 v107, v0
	v_mov_b32_e32 v108, v0
	v_mov_b32_e32 v109, v0
	v_mov_b32_e32 v110, v0
	v_mov_b32_e32 v111, v0
	v_mov_b32_e32 v124, v0
	v_mov_b32_e32 v125, v0
	v_mov_b32_e32 v126, v0
	v_mov_b32_e32 v127, v0
	v_mov_b32_e32 v120, v0
	v_mov_b32_e32 v121, v0
	v_mov_b32_e32 v122, v0
	v_mov_b32_e32 v123, v0
	v_add_u32_e32 v232, s14, v171
	v_add_u32_e32 v233, s14, v145
; #define PG8_STAGE(bufoff, gbase, voff) do { _Pragma("unroll") for (int _i = 0; _i < 2; ++_i) { unsigned vo_ = (voff)[0]; asm volatile("" : "+v"(vo_));   \
;         __builtin_amdgcn_global_load_lds((const unsigned*)((const char*)(gbase) + (size_t)_i * r64step + vo_), (PG8_LAS unsigned*)(lds + (bufoff) + ldsw + _i * 8192), 16, 0, 0); } } while (0)
; #define PG8_WAIT_V(n) asm volatile("s_waitcnt vmcnt(" #n ")" ::: "memory")
; #define PG8_WAIT_L(n) asm volatile("s_waitcnt lgkmcnt(" #n ")" ::: "memory")
; #define PG8_BAR __builtin_amdgcn_s_barrier()
; #define PG8_SCHED __builtin_amdgcn_sched_barrier(0)
; template <class Epi, class Sched, bool ALIGN_EPI = false, bool SP2 = false, bool F8 = false>
; __device__ __forceinline__ void gemm_phase(PG8_LAS unsigned char* lds, const Gemm g, const Sched& S, const Epi& E) {
;     ...
;             PG8_LDB(B0, 0, 0); PG8_LDB(B1, 0, 1); PG8_SCHED; PG8_LDA(At, 0, 0); PG8_STAGE(PG8_SA(1, 1), a1 + hstep, voffA);
;             PG8_WAIT_V(8); PG8_WAIT_L(0); PG8_BAR; PG8_MMA(0, 0, At, B0); PG8_MMA(0, 1, At, B1); PG8_BAR; PG8_SCHED;
;             PG8_LDA(At, 0, 1); PG8_STAGE(PG8_SB(0, 0), b2, voffB); PG8_STAGE(PG8_SB(0, 1), b2 + hstep, voffB); PG8_STAGE(PG8_SA(0, 0), a2, voffA);
;             PG8_WAIT_V(8); PG8_WAIT_L(0); PG8_BAR; PG8_MMA(1, 0, At, B0); PG8_MMA(1, 1, At, B1); PG8_BAR; PG8_SCHED;
.LBB0_179:
	ds_read_b128 v[128:131], v175
	ds_read_b128 v[132:135], v175 offset:1024
	ds_read_b128 v[136:139], v175 offset:2048
	ds_read_b128 v[140:143], v175 offset:3072
	ds_read_b128 v[154:157], v176
	ds_read_b128 v[158:161], v176 offset:1024
	ds_read_b128 v[162:165], v176 offset:2048
	ds_read_b128 v[166:169], v176 offset:3072
	s_add_i32 s80, s30, 2
	s_add_u32 s34, s72, 0x80
	s_addc_u32 s31, s73, 0
	s_cmp_eq_u32 s58, s30
	s_cselect_b32 s30, s0, s34
	s_cselect_b32 s31, s1, s31
	s_cselect_b32 s35, s29, s75
	s_cselect_b32 s34, s28, s74
	s_add_u32 s36, s72, s12
	s_addc_u32 s37, s73, s13
	s_add_i32 m0, s49, 0xc000
	ds_read_b128 v[180:183], v177
	ds_read_b128 v[184:187], v177 offset:1024
	ds_read_b128 v[188:191], v177 offset:2048
	ds_read_b128 v[192:195], v177 offset:3072
	ds_read_b128 v[196:199], v177 offset:4096
	ds_read_b128 v[200:203], v177 offset:5120
	ds_read_b128 v[204:207], v177 offset:6144
	ds_read_b128 v[208:211], v177 offset:7168
	s_nop 0
	global_load_lds_dwordx4 v145, s[36:37]
	s_add_u32 s36, s72, s63
	s_addc_u32 s37, s73, s62
	s_add_i32 m0, s49, 0xe000
	s_nop 0
	global_load_lds_dwordx4 v145, s[36:37]
	s_waitcnt vmcnt(8)
	s_waitcnt lgkmcnt(0)
	s_barrier
	s_setprio 1
	s_waitcnt lgkmcnt(0)
	v_mfma_scale_f32_16x16x128_f8f6f4 v[120:123], v[128:135], v[180:187], v[120:123], v178, v178 op_sel_hi:[0,0,0]
	v_mfma_scale_f32_16x16x128_f8f6f4 v[124:127], v[136:143], v[180:187], v[124:127], v178, v178 op_sel_hi:[0,0,0]
	v_mfma_scale_f32_16x16x128_f8f6f4 v[108:111], v[128:135], v[188:195], v[108:111], v178, v178 op_sel_hi:[0,0,0]
	v_mfma_scale_f32_16x16x128_f8f6f4 v[104:107], v[136:143], v[188:195], v[104:107], v178, v178 op_sel_hi:[0,0,0]
	v_mfma_scale_f32_16x16x128_f8f6f4 v[212:215], v[128:135], v[196:203], v[92:95], v178, v178 op_sel_hi:[0,0,0]
	v_mfma_scale_f32_16x16x128_f8f6f4 v[216:219], v[136:143], v[196:203], v[88:91], v178, v178 op_sel_hi:[0,0,0]
	v_mfma_scale_f32_16x16x128_f8f6f4 v[220:223], v[128:135], v[204:211], v[76:79], v178, v178 op_sel_hi:[0,0,0]
	v_mfma_scale_f32_16x16x128_f8f6f4 v[224:227], v[136:143], v[204:211], v[72:75], v178, v178 op_sel_hi:[0,0,0]
	s_setprio 0
	s_setprio 1
	v_mfma_scale_f32_16x16x128_f8f6f4 v[116:119], v[154:161], v[180:187], v[116:119], v178, v178 op_sel_hi:[0,0,0]
	v_mfma_scale_f32_16x16x128_f8f6f4 v[112:115], v[162:169], v[180:187], v[112:115], v178, v178 op_sel_hi:[0,0,0]
	v_mfma_scale_f32_16x16x128_f8f6f4 v[100:103], v[154:161], v[188:195], v[100:103], v178, v178 op_sel_hi:[0,0,0]
	v_mfma_scale_f32_16x16x128_f8f6f4 v[96:99], v[162:169], v[188:195], v[96:99], v178, v178 op_sel_hi:[0,0,0]
	v_mfma_scale_f32_16x16x128_f8f6f4 v[228:231], v[154:161], v[196:203], v[84:87], v178, v178 op_sel_hi:[0,0,0]
	v_mfma_scale_f32_16x16x128_f8f6f4 v[196:199], v[162:169], v[196:203], v[80:83], v178, v178 op_sel_hi:[0,0,0]
	v_mfma_scale_f32_16x16x128_f8f6f4 v[200:203], v[154:161], v[204:211], v[68:71], v178, v178 op_sel_hi:[0,0,0]
	v_mfma_scale_f32_16x16x128_f8f6f4 v[204:207], v[162:169], v[204:211], v[64:67], v178, v178 op_sel_hi:[0,0,0]
	s_setprio 0
	s_barrier
	s_add_i32 s38, s64, s46
	s_nop 2
	ds_read_b128 v[64:67], v177 offset:16384
	ds_read_b128 v[68:71], v177 offset:17408
	ds_read_b128 v[72:75], v177 offset:18432
	ds_read_b128 v[76:79], v177 offset:19456
	ds_read_b128 v[80:83], v177 offset:20480
	ds_read_b128 v[84:87], v177 offset:21504
	ds_read_b128 v[88:91], v177 offset:22528
	ds_read_b128 v[92:95], v177 offset:23552
	s_mov_b32 m0, s38
	s_add_u32 s36, s34, s6
	global_load_lds_dwordx4 v171, s[34:35]
	s_addc_u32 s37, s35, s7
	s_add_i32 m0, s38, 0x2000
	s_add_u32 s38, s36, s6
	global_load_lds_dwordx4 v171, s[36:37]
	s_addc_u32 s39, s37, s7
	s_add_i32 s40, s65, s46
	s_mov_b32 m0, s40
	s_add_u32 s36, s38, s6
	global_load_lds_dwordx4 v171, s[38:39]
	s_addc_u32 s37, s39, s7
	s_add_i32 m0, s40, 0x2000
	s_add_u32 s40, s30, s6
	global_load_lds_dwordx4 v171, s[36:37]
	s_mov_b32 m0, s49
	s_addc_u32 s41, s31, s7
	global_load_lds_dwordx4 v145, s[30:31]
	s_mov_b32 m0, s50
	s_nop 0
	global_load_lds_dwordx4 v145, s[40:41]
	s_waitcnt vmcnt(8)
	s_waitcnt lgkmcnt(0)
	s_barrier
	s_setprio 1
	s_waitcnt lgkmcnt(0)
	v_mfma_scale_f32_16x16x128_f8f6f4 v[60:63], v[128:135], v[64:71], v[60:63], v178, v178 op_sel_hi:[0,0,0]
	v_mfma_scale_f32_16x16x128_f8f6f4 v[56:59], v[136:143], v[64:71], v[56:59], v178, v178 op_sel_hi:[0,0,0]
	v_mfma_scale_f32_16x16x128_f8f6f4 v[44:47], v[128:135], v[72:79], v[44:47], v178, v178 op_sel_hi:[0,0,0]
	v_mfma_scale_f32_16x16x128_f8f6f4 v[40:43], v[136:143], v[72:79], v[40:43], v178, v178 op_sel_hi:[0,0,0]
	v_mfma_scale_f32_16x16x128_f8f6f4 v[28:31], v[128:135], v[80:87], v[28:31], v178, v178 op_sel_hi:[0,0,0]
	v_mfma_scale_f32_16x16x128_f8f6f4 v[24:27], v[136:143], v[80:87], v[24:27], v178, v178 op_sel_hi:[0,0,0]
	v_mfma_scale_f32_16x16x128_f8f6f4 v[12:15], v[128:135], v[88:95], v[12:15], v178, v178 op_sel_hi:[0,0,0]
	v_mfma_scale_f32_16x16x128_f8f6f4 v[8:11], v[136:143], v[88:95], v[8:11], v178, v178 op_sel_hi:[0,0,0]
	s_setprio 0
	s_setprio 1
	v_mfma_scale_f32_16x16x128_f8f6f4 v[52:55], v[154:161], v[64:71], v[52:55], v178, v178 op_sel_hi:[0,0,0]
	v_mfma_scale_f32_16x16x128_f8f6f4 v[48:51], v[162:169], v[64:71], v[48:51], v178, v178 op_sel_hi:[0,0,0]
	v_mfma_scale_f32_16x16x128_f8f6f4 v[36:39], v[154:161], v[72:79], v[36:39], v178, v178 op_sel_hi:[0,0,0]
	v_mfma_scale_f32_16x16x128_f8f6f4 v[32:35], v[162:169], v[72:79], v[32:35], v178, v178 op_sel_hi:[0,0,0]
	v_mfma_scale_f32_16x16x128_f8f6f4 v[20:23], v[154:161], v[80:87], v[20:23], v178, v178 op_sel_hi:[0,0,0]
	v_mfma_scale_f32_16x16x128_f8f6f4 v[16:19], v[162:169], v[80:87], v[16:19], v178, v178 op_sel_hi:[0,0,0]
	v_mfma_scale_f32_16x16x128_f8f6f4 v[4:7], v[154:161], v[88:95], v[4:7], v178, v178 op_sel_hi:[0,0,0]
	v_mfma_scale_f32_16x16x128_f8f6f4 v[0:3], v[162:169], v[88:95], v[0:3], v178, v178 op_sel_hi:[0,0,0]
	s_setprio 0
	s_barrier
; #define PG8_STAGE(bufoff, gbase, voff) do { _Pragma("unroll") for (int _i = 0; _i < 2; ++_i) { unsigned vo_ = (voff)[0]; asm volatile("" : "+v"(vo_));   \
;         __builtin_amdgcn_global_load_lds((const unsigned*)((const char*)(gbase) + (size_t)_i * r64step + vo_), (PG8_LAS unsigned*)(lds + (bufoff) + ldsw + _i * 8192), 16, 0, 0); } } while (0)
; #define PG8_WAIT_V(n) asm volatile("s_waitcnt vmcnt(" #n ")" ::: "memory")
; #define PG8_WAIT_L(n) asm volatile("s_waitcnt lgkmcnt(" #n ")" ::: "memory")
; #define PG8_BAR __builtin_amdgcn_s_barrier()
; #define PG8_SCHED __builtin_amdgcn_sched_barrier(0)
; template <class Epi, class Sched, bool ALIGN_EPI = false, bool SP2 = false, bool F8 = false>
; __device__ __forceinline__ void gemm_phase(PG8_LAS unsigned char* lds, const Gemm g, const Sched& S, const Epi& E) {
;     ...
;             PG8_LDB(B0, 1, 0); PG8_LDB(B1, 1, 1); PG8_SCHED; PG8_LDA(At, 1, 0); PG8_STAGE(PG8_SA(0, 1), a2 + hstep, voffA);
;             PG8_WAIT_V(8); PG8_WAIT_L(0); PG8_BAR; PG8_MMA(0, 0, At, B0); PG8_MMA(0, 1, At, B1); PG8_BAR; PG8_SCHED;
;             PG8_LDA(At, 1, 1); PG8_STAGE(PG8_SB(1, 0), b3, voffB); PG8_STAGE(PG8_SB(1, 1), b3 + hstep, voffB); PG8_STAGE(PG8_SA(1, 0), a3, voffA);
;             PG8_WAIT_V(8); PG8_WAIT_L(0); PG8_BAR; PG8_MMA(1, 0, At, B0); PG8_MMA(1, 1, At, B1); PG8_BAR; PG8_SCHED;
	s_add_i32 s81, 0, 0x18000
	v_add_u32_e32 v64, s81, v173
	s_add_i32 s84, 0, 0x1c000
	ds_read_b128 v[128:131], v64
	ds_read_b128 v[132:135], v64 offset:1024
	ds_read_b128 v[136:139], v64 offset:2048
	ds_read_b128 v[140:143], v64 offset:3072
	v_add_u32_e32 v64, s84, v173
	ds_read_b128 v[154:157], v64
	ds_read_b128 v[158:161], v64 offset:1024
	ds_read_b128 v[162:165], v64 offset:2048
	ds_read_b128 v[166:169], v64 offset:3072
	s_add_u32 s40, s40, s6
	s_addc_u32 s41, s41, s7
	s_mov_b32 m0, s51
	ds_read_b128 v[64:67], v177 offset:32768
	ds_read_b128 v[68:71], v177 offset:33792
	ds_read_b128 v[80:83], v177 offset:34816
	ds_read_b128 v[84:87], v177 offset:35840
	ds_read_b128 v[180:183], v177 offset:36864
	ds_read_b128 v[184:187], v177 offset:37888
	ds_read_b128 v[188:191], v177 offset:38912
	ds_read_b128 v[192:195], v177 offset:39936
	s_add_u32 s82, s40, s6
	global_load_lds_dwordx4 v145, s[40:41]
	s_addc_u32 s83, s41, s7
	s_mov_b32 m0, s52
	s_nop 0
	global_load_lds_dwordx4 v145, s[82:83]
	s_waitcnt vmcnt(8)
	s_waitcnt lgkmcnt(0)
	s_barrier
	s_setprio 1
	s_waitcnt lgkmcnt(0)
	v_mfma_scale_f32_16x16x128_f8f6f4 v[120:123], v[128:135], v[64:71], v[120:123], v178, v178 op_sel_hi:[0,0,0]
	v_mfma_scale_f32_16x16x128_f8f6f4 v[124:127], v[136:143], v[64:71], v[124:127], v178, v178 op_sel_hi:[0,0,0]
	v_mfma_scale_f32_16x16x128_f8f6f4 v[108:111], v[128:135], v[80:87], v[108:111], v178, v178 op_sel_hi:[0,0,0]
	v_mfma_scale_f32_16x16x128_f8f6f4 v[104:107], v[136:143], v[80:87], v[104:107], v178, v178 op_sel_hi:[0,0,0]
	v_mfma_scale_f32_16x16x128_f8f6f4 v[92:95], v[128:135], v[180:187], v[212:215], v178, v178 op_sel_hi:[0,0,0]
	v_mfma_scale_f32_16x16x128_f8f6f4 v[88:91], v[136:143], v[180:187], v[216:219], v178, v178 op_sel_hi:[0,0,0]
	v_mfma_scale_f32_16x16x128_f8f6f4 v[76:79], v[128:135], v[188:195], v[220:223], v178, v178 op_sel_hi:[0,0,0]
	v_mfma_scale_f32_16x16x128_f8f6f4 v[72:75], v[136:143], v[188:195], v[224:227], v178, v178 op_sel_hi:[0,0,0]
	s_setprio 0
	s_setprio 1
	v_mfma_scale_f32_16x16x128_f8f6f4 v[116:119], v[154:161], v[64:71], v[116:119], v178, v178 op_sel_hi:[0,0,0]
	v_mfma_scale_f32_16x16x128_f8f6f4 v[112:115], v[162:169], v[64:71], v[112:115], v178, v178 op_sel_hi:[0,0,0]
	v_mfma_scale_f32_16x16x128_f8f6f4 v[100:103], v[154:161], v[80:87], v[100:103], v178, v178 op_sel_hi:[0,0,0]
	v_mfma_scale_f32_16x16x128_f8f6f4 v[96:99], v[162:169], v[80:87], v[96:99], v178, v178 op_sel_hi:[0,0,0]
	v_mfma_scale_f32_16x16x128_f8f6f4 v[84:87], v[154:161], v[180:187], v[228:231], v178, v178 op_sel_hi:[0,0,0]
	v_mfma_scale_f32_16x16x128_f8f6f4 v[80:83], v[162:169], v[180:187], v[196:199], v178, v178 op_sel_hi:[0,0,0]
	v_mfma_scale_f32_16x16x128_f8f6f4 v[68:71], v[154:161], v[188:195], v[200:203], v178, v178 op_sel_hi:[0,0,0]
	v_mfma_scale_f32_16x16x128_f8f6f4 v[64:67], v[162:169], v[188:195], v[204:207], v178, v178 op_sel_hi:[0,0,0]
	s_setprio 0
	s_barrier
	ds_read_b128 v[180:183], v177 offset:49152
	ds_read_b128 v[184:187], v177 offset:50176
	ds_read_b128 v[188:191], v177 offset:51200
	ds_read_b128 v[192:195], v177 offset:52224
	ds_read_b128 v[196:199], v177 offset:53248
	ds_read_b128 v[200:203], v177 offset:54272
	ds_read_b128 v[204:207], v177 offset:55296
	ds_read_b128 v[208:211], v177 offset:56320
	s_add_i32 s81, s81, s46
	s_add_u32 s100, s34, s14
	s_addc_u32 s101, s35, s15
	s_mov_b32 m0, s81
	s_add_u32 s34, s38, s25
	global_load_lds_dwordx4 v171, s[100:101]
	s_addc_u32 s35, s39, s55
	s_add_i32 m0, s81, 0x2000
	s_nop 0
	s_add_u32 s100, s34, s14
	s_addc_u32 s101, s35, s15
	s_add_u32 s34, s34, s6
	s_addc_u32 s35, s35, s7
	global_load_lds_dwordx4 v171, s[100:101]
	s_nop 0
	s_add_u32 s100, s34, s14
	s_addc_u32 s101, s35, s15
	s_add_i32 s34, s84, s46
	s_mov_b32 m0, s34
	s_nop 0
	global_load_lds_dwordx4 v171, s[100:101]
	s_add_i32 m0, s34, 0x2000
	s_nop 0
	global_load_lds_dwordx4 v232, s[36:37]
	s_mov_b32 m0, s56
	s_add_u32 s100, s30, s14
	s_addc_u32 s101, s31, s15
	s_add_u32 s30, s40, s25
	s_addc_u32 s31, s41, s55
	global_load_lds_dwordx4 v145, s[100:101]
	s_mov_b32 m0, s57
	s_nop 0
	global_load_lds_dwordx4 v233, s[30:31]
	s_waitcnt vmcnt(8)
	s_waitcnt lgkmcnt(0)
	s_barrier
	s_setprio 1
	s_waitcnt lgkmcnt(0)
	v_mfma_scale_f32_16x16x128_f8f6f4 v[60:63], v[128:135], v[180:187], v[60:63], v178, v178 op_sel_hi:[0,0,0]
	v_mfma_scale_f32_16x16x128_f8f6f4 v[56:59], v[136:143], v[180:187], v[56:59], v178, v178 op_sel_hi:[0,0,0]
	v_mfma_scale_f32_16x16x128_f8f6f4 v[44:47], v[128:135], v[188:195], v[44:47], v178, v178 op_sel_hi:[0,0,0]
	v_mfma_scale_f32_16x16x128_f8f6f4 v[40:43], v[136:143], v[188:195], v[40:43], v178, v178 op_sel_hi:[0,0,0]
	v_mfma_scale_f32_16x16x128_f8f6f4 v[28:31], v[128:135], v[196:203], v[28:31], v178, v178 op_sel_hi:[0,0,0]
	v_mfma_scale_f32_16x16x128_f8f6f4 v[24:27], v[136:143], v[196:203], v[24:27], v178, v178 op_sel_hi:[0,0,0]
	v_mfma_scale_f32_16x16x128_f8f6f4 v[12:15], v[128:135], v[204:211], v[12:15], v178, v178 op_sel_hi:[0,0,0]
	v_mfma_scale_f32_16x16x128_f8f6f4 v[8:11], v[136:143], v[204:211], v[8:11], v178, v178 op_sel_hi:[0,0,0]
	s_setprio 0
	s_setprio 1
	v_mfma_scale_f32_16x16x128_f8f6f4 v[52:55], v[154:161], v[180:187], v[52:55], v178, v178 op_sel_hi:[0,0,0]
	v_mfma_scale_f32_16x16x128_f8f6f4 v[48:51], v[162:169], v[180:187], v[48:51], v178, v178 op_sel_hi:[0,0,0]
	v_mfma_scale_f32_16x16x128_f8f6f4 v[36:39], v[154:161], v[188:195], v[36:39], v178, v178 op_sel_hi:[0,0,0]
	v_mfma_scale_f32_16x16x128_f8f6f4 v[32:35], v[162:169], v[188:195], v[32:35], v178, v178 op_sel_hi:[0,0,0]
	v_mfma_scale_f32_16x16x128_f8f6f4 v[20:23], v[154:161], v[196:203], v[20:23], v178, v178 op_sel_hi:[0,0,0]
	v_mfma_scale_f32_16x16x128_f8f6f4 v[16:19], v[162:169], v[196:203], v[16:19], v178, v178 op_sel_hi:[0,0,0]
	v_mfma_scale_f32_16x16x128_f8f6f4 v[4:7], v[154:161], v[204:211], v[4:7], v178, v178 op_sel_hi:[0,0,0]
	v_mfma_scale_f32_16x16x128_f8f6f4 v[0:3], v[162:169], v[204:211], v[0:3], v178, v178 op_sel_hi:[0,0,0]
	s_setprio 0
	s_barrier
	s_add_u32 s72, s72, 0x100
	s_addc_u32 s73, s73, 0
	s_add_u32 s74, s74, 0x100
	s_addc_u32 s75, s75, 0
	s_cmp_ge_i32 s80, s54
	s_mov_b32 s30, s80
	s_cbranch_scc0 .LBB0_179
	s_mov_b64 s[82:83], vcc

; template <class Epi, class Sched, bool ALIGN_EPI = false, bool SP2 = false, bool F8 = false>
; __device__ __forceinline__ void gemm_phase(PG8_LAS unsigned char* lds, const Gemm g, const Sched& S, const Epi& E) {
;     ...
;             if constexpr (Epi::HOOK_T >= 0) { if (t == Epi::HOOK_T) E.mid(acc, cur, wr, wc, fr, fq); }
;     ...
; #pragma unroll
;         for (int a = 0; a < 2; ++a)
; #pragma unroll
;             for (int b = 0; b < 2; ++b)
; #pragma unroll
;                 for (int m = 0; m < 4; ++m)
; #pragma unroll
;                     for (int n = 0; n < 2; ++n) acc[a][b][m][n] = (f32x4){0.f, 0.f, 0.f, 0.f};
.LBB0_416:
	v_mov_b32_e32 v131, 0
	s_andn2_b64 vcc, exec, s[16:17]
	v_lshl_or_b32 v136, s28, 8, v151
	v_mov_b32_e32 v130, 0
	v_mov_b32_e32 v129, 0
	v_mov_b32_e32 v128, 0
	v_mov_b32_e32 v127, 0
	v_mov_b32_e32 v126, 0
	v_mov_b32_e32 v125, 0
	v_mov_b32_e32 v124, 0
	v_mov_b32_e32 v113, 0
	v_mov_b32_e32 v112, 0
	v_mov_b32_e32 v115, 0
	v_mov_b32_e32 v114, 0
	v_mov_b32_e32 v111, 0
	v_mov_b32_e32 v110, 0
	v_mov_b32_e32 v109, 0
	v_mov_b32_e32 v108, 0
	v_mov_b32_e32 v97, 0
	v_mov_b32_e32 v96, 0
	v_mov_b32_e32 v99, 0
	v_mov_b32_e32 v98, 0
	v_mov_b32_e32 v95, 0
	v_mov_b32_e32 v94, 0
	v_mov_b32_e32 v93, 0
	v_mov_b32_e32 v92, 0
	v_mov_b32_e32 v81, 0
	v_mov_b32_e32 v80, 0
	v_mov_b32_e32 v83, 0
	v_mov_b32_e32 v82, 0
	v_mov_b32_e32 v79, 0
	v_mov_b32_e32 v78, 0
	v_mov_b32_e32 v77, 0
	v_mov_b32_e32 v76, 0
	v_mov_b32_e32 v139, 0
	v_mov_b32_e32 v138, 0
	v_mov_b32_e32 v141, 0
	v_mov_b32_e32 v140, 0
	v_mov_b32_e32 v143, 0
	v_mov_b32_e32 v142, 0
	v_mov_b32_e32 v147, 0
	v_mov_b32_e32 v146, 0
	v_mov_b32_e32 v117, 0
	v_mov_b32_e32 v116, 0
	v_mov_b32_e32 v119, 0
	v_mov_b32_e32 v118, 0
	v_mov_b32_e32 v121, 0
	v_mov_b32_e32 v120, 0
	v_mov_b32_e32 v123, 0
	v_mov_b32_e32 v122, 0
	v_mov_b32_e32 v101, 0
	v_mov_b32_e32 v100, 0
	v_mov_b32_e32 v103, 0
	v_mov_b32_e32 v102, 0
	v_mov_b32_e32 v105, 0
	v_mov_b32_e32 v104, 0
	v_mov_b32_e32 v107, 0
	v_mov_b32_e32 v106, 0
	v_mov_b32_e32 v85, 0
	v_mov_b32_e32 v84, 0
	v_mov_b32_e32 v87, 0
	v_mov_b32_e32 v86, 0
	v_mov_b32_e32 v89, 0
	v_mov_b32_e32 v88, 0
	v_mov_b32_e32 v91, 0
	v_mov_b32_e32 v90, 0
	v_mov_b32_e32 v61, 0
	v_mov_b32_e32 v60, 0
	v_mov_b32_e32 v63, 0
	v_mov_b32_e32 v62, 0
	v_mov_b32_e32 v65, 0
	v_mov_b32_e32 v64, 0
	v_mov_b32_e32 v67, 0
	v_mov_b32_e32 v66, 0
	v_mov_b32_e32 v49, 0
	v_mov_b32_e32 v48, 0
	v_mov_b32_e32 v51, 0
	v_mov_b32_e32 v50, 0
	v_mov_b32_e32 v47, 0
	v_mov_b32_e32 v46, 0
	v_mov_b32_e32 v45, 0
	v_mov_b32_e32 v44, 0
	v_mov_b32_e32 v33, 0
	v_mov_b32_e32 v32, 0
	v_mov_b32_e32 v35, 0
	v_mov_b32_e32 v34, 0
	v_mov_b32_e32 v31, 0
	v_mov_b32_e32 v30, 0
	v_mov_b32_e32 v29, 0
	v_mov_b32_e32 v28, 0
	v_mov_b32_e32 v17, 0
	v_mov_b32_e32 v16, 0
	v_mov_b32_e32 v19, 0
	v_mov_b32_e32 v18, 0
	v_mov_b32_e32 v15, 0
	v_mov_b32_e32 v14, 0
	v_mov_b32_e32 v13, 0
	v_mov_b32_e32 v12, 0
	v_mov_b32_e32 v59, 0
	v_mov_b32_e32 v58, 0
	v_mov_b32_e32 v57, 0
	v_mov_b32_e32 v56, 0
	v_mov_b32_e32 v69, 0
	v_mov_b32_e32 v68, 0
	v_mov_b32_e32 v71, 0
	v_mov_b32_e32 v70, 0
	v_mov_b32_e32 v43, 0
	v_mov_b32_e32 v42, 0
	v_mov_b32_e32 v41, 0
	v_mov_b32_e32 v40, 0
	v_mov_b32_e32 v53, 0
	v_mov_b32_e32 v52, 0
	v_mov_b32_e32 v55, 0
	v_mov_b32_e32 v54, 0
	v_mov_b32_e32 v27, 0
	v_mov_b32_e32 v26, 0
	v_mov_b32_e32 v37, 0
	v_mov_b32_e32 v36, 0
	v_mov_b32_e32 v25, 0
	v_mov_b32_e32 v24, 0
	v_mov_b32_e32 v39, 0
	v_mov_b32_e32 v38, 0
	v_mov_b32_e32 v11, 0
	v_mov_b32_e32 v10, 0
	v_mov_b32_e32 v9, 0
	v_mov_b32_e32 v8, 0
	v_mov_b32_e32 v3, 0
	v_mov_b32_e32 v2, 0
	v_mov_b32_e32 v5, 0
	v_mov_b32_e32 v4, 0
	s_cbranch_vccnz .LBB0_422
	s_add_u32 s68, s26, 0x100
	s_addc_u32 s69, s27, 0
	s_add_u32 s70, s24, s12
	s_addc_u32 s71, s25, s13
	v_mov_b32_e32 v2, v1
	v_mov_b32_e32 v3, v1
	v_ashrrev_i32_e32 v137, 31, v136
	s_add_u32 s72, s24, s57
	v_mov_b32_e32 v0, v1
	v_mov_b64_e32 v[6:7], v[2:3]
	v_mov_b64_e32 v[10:11], v[2:3]
	v_mov_b64_e32 v[18:19], v[2:3]
	v_mov_b64_e32 v[26:27], v[2:3]
	v_mov_b64_e32 v[34:35], v[2:3]
	v_mov_b64_e32 v[42:43], v[2:3]
	v_mov_b64_e32 v[50:51], v[2:3]
	v_mov_b64_e32 v[58:59], v[2:3]
	v_mov_b64_e32 v[14:15], v[2:3]
	v_mov_b64_e32 v[22:23], v[2:3]
	v_mov_b64_e32 v[30:31], v[2:3]
	v_mov_b64_e32 v[38:39], v[2:3]
	v_mov_b64_e32 v[46:47], v[2:3]
	v_mov_b64_e32 v[54:55], v[2:3]
	v_mov_b64_e32 v[70:71], v[2:3]
	v_mov_b64_e32 v[74:75], v[2:3]
	v_mov_b64_e32 v[62:63], v[2:3]
	v_mov_b64_e32 v[66:67], v[2:3]
	v_mov_b64_e32 v[82:83], v[2:3]
	v_mov_b64_e32 v[90:91], v[2:3]
	v_mov_b64_e32 v[98:99], v[2:3]
	v_mov_b64_e32 v[106:107], v[2:3]
	v_mov_b64_e32 v[114:115], v[2:3]
	v_mov_b64_e32 v[122:123], v[2:3]
	v_mov_b64_e32 v[78:79], v[2:3]
	v_mov_b64_e32 v[86:87], v[2:3]
	v_mov_b64_e32 v[94:95], v[2:3]
	v_mov_b64_e32 v[102:103], v[2:3]
	v_mov_b64_e32 v[110:111], v[2:3]
	v_mov_b64_e32 v[118:119], v[2:3]
	v_mov_b64_e32 v[126:127], v[2:3]
	v_mov_b64_e32 v[130:131], v[2:3]
	v_lshl_add_u32 v140, s67, 8, v149
	v_lshl_add_u64 v[138:139], s[84:85], 0, v[136:137]
	s_addc_u32 s73, s25, s58
	s_mov_b32 s28, 0
	s_mov_b64 s[26:27], 0
	v_mov_b64_e32 v[4:5], v[0:1]
	v_mov_b64_e32 v[8:9], v[0:1]
	v_mov_b64_e32 v[16:17], v[0:1]
	v_mov_b64_e32 v[24:25], v[0:1]
	v_mov_b64_e32 v[32:33], v[0:1]
	v_mov_b64_e32 v[40:41], v[0:1]
	v_mov_b64_e32 v[48:49], v[0:1]
	v_mov_b64_e32 v[56:57], v[0:1]
	v_mov_b64_e32 v[12:13], v[0:1]
	v_mov_b64_e32 v[20:21], v[0:1]
	v_mov_b64_e32 v[28:29], v[0:1]
	v_mov_b64_e32 v[36:37], v[0:1]
	v_mov_b64_e32 v[44:45], v[0:1]
	v_mov_b64_e32 v[52:53], v[0:1]
	v_mov_b64_e32 v[68:69], v[0:1]
	v_mov_b64_e32 v[72:73], v[0:1]
	v_mov_b64_e32 v[60:61], v[0:1]
	v_mov_b64_e32 v[64:65], v[0:1]
	v_mov_b64_e32 v[80:81], v[0:1]
	v_mov_b64_e32 v[88:89], v[0:1]
	v_mov_b64_e32 v[96:97], v[0:1]
	v_mov_b64_e32 v[104:105], v[0:1]
	v_mov_b64_e32 v[112:113], v[0:1]
	v_mov_b64_e32 v[120:121], v[0:1]
	v_mov_b64_e32 v[76:77], v[0:1]
	v_mov_b64_e32 v[84:85], v[0:1]
	v_mov_b64_e32 v[92:93], v[0:1]
	v_mov_b64_e32 v[100:101], v[0:1]
	v_mov_b64_e32 v[108:109], v[0:1]
	v_mov_b64_e32 v[116:117], v[0:1]
	v_mov_b64_e32 v[124:125], v[0:1]
	v_mov_b64_e32 v[128:129], v[0:1]
	v_add_u32_e32 v248, s14, v148
	v_add_u32_e32 v249, s14, v145
	s_cmp_lg_u32 s28, 2
	s_cbranch_scc1 .LBB0_419

; #define PG8_STAGE(bufoff, gbase, voff) do { _Pragma("unroll") for (int _i = 0; _i < 2; ++_i) { unsigned vo_ = (voff)[0]; asm volatile("" : "+v"(vo_));   \
;         __builtin_amdgcn_global_load_lds((const unsigned*)((const char*)(gbase) + (size_t)_i * r64step + vo_), (PG8_LAS unsigned*)(lds + (bufoff) + ldsw + _i * 8192), 16, 0, 0); } } while (0)
; #define PG8_WAIT_V(n) asm volatile("s_waitcnt vmcnt(" #n ")" ::: "memory")
; #define PG8_WAIT_L(n) asm volatile("s_waitcnt lgkmcnt(" #n ")" ::: "memory")
; #define PG8_BAR __builtin_amdgcn_s_barrier()
; #define PG8_SCHED __builtin_amdgcn_sched_barrier(0)
; template <class Epi, class Sched, bool ALIGN_EPI = false, bool SP2 = false, bool F8 = false>
; __device__ __forceinline__ void gemm_phase(PG8_LAS unsigned char* lds, const Gemm g, const Sched& S, const Epi& E) {
;     ...
;             PG8_LDB(B0, 0, 0); PG8_LDB(B1, 0, 1); PG8_SCHED; PG8_LDA(At, 0, 0); PG8_STAGE(PG8_SA(1, 1), a1 + hstep, voffA);
;             PG8_WAIT_V(8); PG8_WAIT_L(0); PG8_BAR; PG8_MMA(0, 0, At, B0); PG8_MMA(0, 1, At, B1); PG8_BAR; PG8_SCHED;
;             PG8_LDA(At, 0, 1); PG8_STAGE(PG8_SB(0, 0), b2, voffB); PG8_STAGE(PG8_SB(0, 1), b2 + hstep, voffB); PG8_STAGE(PG8_SA(0, 0), a2, voffA);
;             PG8_WAIT_V(8); PG8_WAIT_L(0); PG8_BAR; PG8_MMA(1, 0, At, B0); PG8_MMA(1, 1, At, B1); PG8_BAR; PG8_SCHED;
.LBB0_419:
	v_add_u32_e32 v0, s59, v150
	s_add_i32 s74, s28, 2
	ds_read_b128 v[154:157], v0
	ds_read_b128 v[158:161], v0 offset:1024
	ds_read_b128 v[162:165], v0 offset:2048
	ds_read_b128 v[166:169], v0 offset:3072
	v_add_u32_e32 v0, s60, v150
	s_add_u32 s29, s24, s26
	ds_read_b128 v[172:175], v0
	ds_read_b128 v[176:179], v0 offset:1024
	ds_read_b128 v[180:183], v0 offset:2048
	ds_read_b128 v[184:187], v0 offset:3072
	s_addc_u32 s30, s25, s27
	s_add_u32 s31, s29, 0x100
	s_addc_u32 s29, s30, 0
	s_add_u32 s30, s68, s26
	s_addc_u32 s34, s69, s27
	s_cmp_eq_u32 s54, s28
	s_cselect_b32 s29, s5, s29
	s_cselect_b32 s28, s4, s31
	s_cselect_b32 s31, s23, s34
	s_cselect_b32 s30, s22, s30
	s_add_u32 s34, s70, s26
	s_addc_u32 s35, s71, s27
	s_add_i32 m0, s42, 0xc000
	ds_read_b128 v[188:191], v152
	ds_read_b128 v[192:195], v152 offset:1024
	ds_read_b128 v[196:199], v152 offset:2048
	ds_read_b128 v[200:203], v152 offset:3072
	ds_read_b128 v[204:207], v152 offset:4096
	ds_read_b128 v[208:211], v152 offset:5120
	ds_read_b128 v[212:215], v152 offset:6144
	ds_read_b128 v[216:219], v152 offset:7168
	s_nop 0
	global_load_lds_dwordx4 v145, s[34:35]
	s_add_u32 s34, s72, s26
	s_addc_u32 s35, s73, s27
	s_add_i32 m0, s42, 0xe000
	s_nop 0
	global_load_lds_dwordx4 v145, s[34:35]
	s_waitcnt vmcnt(8)
	s_waitcnt lgkmcnt(0)
	s_barrier
	s_setprio 1
	s_waitcnt lgkmcnt(0)
	v_mfma_scale_f32_16x16x128_f8f6f4 v[128:131], v[154:161], v[188:195], v[128:131], v153, v153 op_sel_hi:[0,0,0]
	v_mfma_scale_f32_16x16x128_f8f6f4 v[124:127], v[162:169], v[188:195], v[124:127], v153, v153 op_sel_hi:[0,0,0]
	v_mfma_scale_f32_16x16x128_f8f6f4 v[116:119], v[154:161], v[196:203], v[116:119], v153, v153 op_sel_hi:[0,0,0]
	v_mfma_scale_f32_16x16x128_f8f6f4 v[108:111], v[162:169], v[196:203], v[108:111], v153, v153 op_sel_hi:[0,0,0]
	v_mfma_scale_f32_16x16x128_f8f6f4 v[100:103], v[154:161], v[204:211], v[100:103], v153, v153 op_sel_hi:[0,0,0]
	v_mfma_scale_f32_16x16x128_f8f6f4 v[220:223], v[162:169], v[204:211], v[92:95], v153, v153 op_sel_hi:[0,0,0]
	v_mfma_scale_f32_16x16x128_f8f6f4 v[224:227], v[154:161], v[212:219], v[84:87], v153, v153 op_sel_hi:[0,0,0]
	v_mfma_scale_f32_16x16x128_f8f6f4 v[228:231], v[162:169], v[212:219], v[76:79], v153, v153 op_sel_hi:[0,0,0]
	s_setprio 0
	s_setprio 1
	v_mfma_scale_f32_16x16x128_f8f6f4 v[120:123], v[172:179], v[188:195], v[120:123], v153, v153 op_sel_hi:[0,0,0]
	v_mfma_scale_f32_16x16x128_f8f6f4 v[112:115], v[180:187], v[188:195], v[112:115], v153, v153 op_sel_hi:[0,0,0]
	v_mfma_scale_f32_16x16x128_f8f6f4 v[104:107], v[172:179], v[196:203], v[104:107], v153, v153 op_sel_hi:[0,0,0]
	v_mfma_scale_f32_16x16x128_f8f6f4 v[232:235], v[180:187], v[196:203], v[96:99], v153, v153 op_sel_hi:[0,0,0]
	v_mfma_scale_f32_16x16x128_f8f6f4 v[236:239], v[172:179], v[204:211], v[88:91], v153, v153 op_sel_hi:[0,0,0]
	v_mfma_scale_f32_16x16x128_f8f6f4 v[240:243], v[180:187], v[204:211], v[80:83], v153, v153 op_sel_hi:[0,0,0]
	v_mfma_scale_f32_16x16x128_f8f6f4 v[244:247], v[172:179], v[212:219], v[64:67], v153, v153 op_sel_hi:[0,0,0]
	v_mfma_scale_f32_16x16x128_f8f6f4 v[212:215], v[180:187], v[212:219], v[60:63], v153, v153 op_sel_hi:[0,0,0]
	s_setprio 0
	s_barrier
	s_add_i32 s36, s59, s41
	s_nop 2
	ds_read_b128 v[60:63], v152 offset:16384
	ds_read_b128 v[64:67], v152 offset:17408
	ds_read_b128 v[76:79], v152 offset:18432
	ds_read_b128 v[80:83], v152 offset:19456
	ds_read_b128 v[84:87], v152 offset:20480
	ds_read_b128 v[88:91], v152 offset:21504
	ds_read_b128 v[92:95], v152 offset:22528
	ds_read_b128 v[96:99], v152 offset:23552
	s_mov_b32 m0, s36
	s_add_u32 s34, s30, s6
	global_load_lds_dwordx4 v148, s[30:31]
	s_addc_u32 s35, s31, s7
	s_add_i32 m0, s36, 0x2000
	s_add_u32 s36, s34, s6
	global_load_lds_dwordx4 v148, s[34:35]
	s_addc_u32 s37, s35, s7
	s_add_i32 s38, s60, s41
	s_mov_b32 m0, s38
	s_add_u32 s34, s36, s6
	global_load_lds_dwordx4 v148, s[36:37]
	s_addc_u32 s35, s37, s7
	s_add_i32 m0, s38, 0x2000
	s_add_u32 s38, s28, s6
	global_load_lds_dwordx4 v148, s[34:35]
	s_mov_b32 m0, s42
	s_addc_u32 s39, s29, s7
	global_load_lds_dwordx4 v145, s[28:29]
	s_mov_b32 m0, s43
	s_nop 0
	global_load_lds_dwordx4 v145, s[38:39]
	s_waitcnt vmcnt(8)
	s_waitcnt lgkmcnt(0)
	s_barrier
	s_setprio 1
	s_waitcnt lgkmcnt(0)
	v_mfma_scale_f32_16x16x128_f8f6f4 v[72:75], v[154:161], v[60:67], v[72:75], v153, v153 op_sel_hi:[0,0,0]
	v_mfma_scale_f32_16x16x128_f8f6f4 v[68:71], v[162:169], v[60:67], v[68:71], v153, v153 op_sel_hi:[0,0,0]
	v_mfma_scale_f32_16x16x128_f8f6f4 v[52:55], v[154:161], v[76:83], v[52:55], v153, v153 op_sel_hi:[0,0,0]
	v_mfma_scale_f32_16x16x128_f8f6f4 v[44:47], v[162:169], v[76:83], v[44:47], v153, v153 op_sel_hi:[0,0,0]
	v_mfma_scale_f32_16x16x128_f8f6f4 v[36:39], v[154:161], v[84:91], v[36:39], v153, v153 op_sel_hi:[0,0,0]
	v_mfma_scale_f32_16x16x128_f8f6f4 v[28:31], v[162:169], v[84:91], v[28:31], v153, v153 op_sel_hi:[0,0,0]
	v_mfma_scale_f32_16x16x128_f8f6f4 v[20:23], v[154:161], v[92:99], v[20:23], v153, v153 op_sel_hi:[0,0,0]
	v_mfma_scale_f32_16x16x128_f8f6f4 v[12:15], v[162:169], v[92:99], v[12:15], v153, v153 op_sel_hi:[0,0,0]
	s_setprio 0
	s_setprio 1
	v_mfma_scale_f32_16x16x128_f8f6f4 v[56:59], v[172:179], v[60:67], v[56:59], v153, v153 op_sel_hi:[0,0,0]
	v_mfma_scale_f32_16x16x128_f8f6f4 v[48:51], v[180:187], v[60:67], v[48:51], v153, v153 op_sel_hi:[0,0,0]
	v_mfma_scale_f32_16x16x128_f8f6f4 v[40:43], v[172:179], v[76:83], v[40:43], v153, v153 op_sel_hi:[0,0,0]
	v_mfma_scale_f32_16x16x128_f8f6f4 v[32:35], v[180:187], v[76:83], v[32:35], v153, v153 op_sel_hi:[0,0,0]
	v_mfma_scale_f32_16x16x128_f8f6f4 v[24:27], v[172:179], v[84:91], v[24:27], v153, v153 op_sel_hi:[0,0,0]
	v_mfma_scale_f32_16x16x128_f8f6f4 v[16:19], v[180:187], v[84:91], v[16:19], v153, v153 op_sel_hi:[0,0,0]
	v_mfma_scale_f32_16x16x128_f8f6f4 v[8:11], v[172:179], v[92:99], v[8:11], v153, v153 op_sel_hi:[0,0,0]
	v_mfma_scale_f32_16x16x128_f8f6f4 v[2:5], v[180:187], v[92:99], v[4:7], v153, v153 op_sel_hi:[0,0,0]
	s_setprio 0
	s_barrier
; #define PG8_STAGE(bufoff, gbase, voff) do { _Pragma("unroll") for (int _i = 0; _i < 2; ++_i) { unsigned vo_ = (voff)[0]; asm volatile("" : "+v"(vo_));   \
;         __builtin_amdgcn_global_load_lds((const unsigned*)((const char*)(gbase) + (size_t)_i * r64step + vo_), (PG8_LAS unsigned*)(lds + (bufoff) + ldsw + _i * 8192), 16, 0, 0); } } while (0)
; #define PG8_WAIT_V(n) asm volatile("s_waitcnt vmcnt(" #n ")" ::: "memory")
; #define PG8_WAIT_L(n) asm volatile("s_waitcnt lgkmcnt(" #n ")" ::: "memory")
; #define PG8_BAR __builtin_amdgcn_s_barrier()
; #define PG8_SCHED __builtin_amdgcn_sched_barrier(0)
; template <class Epi, class Sched, bool ALIGN_EPI = false, bool SP2 = false, bool F8 = false>
; __device__ __forceinline__ void gemm_phase(PG8_LAS unsigned char* lds, const Gemm g, const Sched& S, const Epi& E) {
;     ...
;             PG8_LDB(B0, 1, 0); PG8_LDB(B1, 1, 1); PG8_SCHED; PG8_LDA(At, 1, 0); PG8_STAGE(PG8_SA(0, 1), a2 + hstep, voffA);
;             PG8_WAIT_V(8); PG8_WAIT_L(0); PG8_BAR; PG8_MMA(0, 0, At, B0); PG8_MMA(0, 1, At, B1); PG8_BAR; PG8_SCHED;
;             PG8_LDA(At, 1, 1); PG8_STAGE(PG8_SB(1, 0), b3, voffB); PG8_STAGE(PG8_SB(1, 1), b3 + hstep, voffB); PG8_STAGE(PG8_SA(1, 0), a3, voffA);
;             PG8_WAIT_V(8); PG8_WAIT_L(0); PG8_BAR; PG8_MMA(1, 0, At, B0); PG8_MMA(1, 1, At, B1); PG8_BAR; PG8_SCHED;
	s_add_i32 s75, 0, 0x18000
	v_add_u32_e32 v0, s75, v150
	s_add_i32 s80, 0, 0x1c000
	ds_read_b128 v[154:157], v0
	ds_read_b128 v[158:161], v0 offset:1024
	ds_read_b128 v[162:165], v0 offset:2048
	ds_read_b128 v[166:169], v0 offset:3072
	v_add_u32_e32 v0, s80, v150
	ds_read_b128 v[172:175], v0
	ds_read_b128 v[176:179], v0 offset:1024
	ds_read_b128 v[180:183], v0 offset:2048
	ds_read_b128 v[184:187], v0 offset:3072
	s_add_u32 s38, s38, s6
	s_addc_u32 s39, s39, s7
	s_mov_b32 m0, s44
	ds_read_b128 v[60:63], v152 offset:32768
	ds_read_b128 v[64:67], v152 offset:33792
	ds_read_b128 v[188:191], v152 offset:34816
	ds_read_b128 v[192:195], v152 offset:35840
	ds_read_b128 v[196:199], v152 offset:36864
	ds_read_b128 v[200:203], v152 offset:37888
	ds_read_b128 v[204:207], v152 offset:38912
	ds_read_b128 v[208:211], v152 offset:39936
	s_add_u32 s78, s38, s6
	global_load_lds_dwordx4 v145, s[38:39]
	s_addc_u32 s79, s39, s7
	s_mov_b32 m0, s45
	s_nop 0
	global_load_lds_dwordx4 v145, s[78:79]
	s_waitcnt vmcnt(8)
	s_waitcnt lgkmcnt(0)
	s_barrier
	s_setprio 1
	s_waitcnt lgkmcnt(0)
	v_mfma_scale_f32_16x16x128_f8f6f4 v[128:131], v[154:161], v[60:67], v[128:131], v153, v153 op_sel_hi:[0,0,0]
	v_mfma_scale_f32_16x16x128_f8f6f4 v[124:127], v[162:169], v[60:67], v[124:127], v153, v153 op_sel_hi:[0,0,0]
	v_mfma_scale_f32_16x16x128_f8f6f4 v[116:119], v[154:161], v[188:195], v[116:119], v153, v153 op_sel_hi:[0,0,0]
	v_mfma_scale_f32_16x16x128_f8f6f4 v[108:111], v[162:169], v[188:195], v[108:111], v153, v153 op_sel_hi:[0,0,0]
	v_mfma_scale_f32_16x16x128_f8f6f4 v[100:103], v[154:161], v[196:203], v[100:103], v153, v153 op_sel_hi:[0,0,0]
	v_mfma_scale_f32_16x16x128_f8f6f4 v[92:95], v[162:169], v[196:203], v[220:223], v153, v153 op_sel_hi:[0,0,0]
	v_mfma_scale_f32_16x16x128_f8f6f4 v[84:87], v[154:161], v[204:211], v[224:227], v153, v153 op_sel_hi:[0,0,0]
	v_mfma_scale_f32_16x16x128_f8f6f4 v[76:79], v[162:169], v[204:211], v[228:231], v153, v153 op_sel_hi:[0,0,0]
	s_setprio 0
	s_setprio 1
	v_mfma_scale_f32_16x16x128_f8f6f4 v[120:123], v[172:179], v[60:67], v[120:123], v153, v153 op_sel_hi:[0,0,0]
	v_mfma_scale_f32_16x16x128_f8f6f4 v[112:115], v[180:187], v[60:67], v[112:115], v153, v153 op_sel_hi:[0,0,0]
	v_mfma_scale_f32_16x16x128_f8f6f4 v[104:107], v[172:179], v[188:195], v[104:107], v153, v153 op_sel_hi:[0,0,0]
	v_mfma_scale_f32_16x16x128_f8f6f4 v[96:99], v[180:187], v[188:195], v[232:235], v153, v153 op_sel_hi:[0,0,0]
	v_mfma_scale_f32_16x16x128_f8f6f4 v[88:91], v[172:179], v[196:203], v[236:239], v153, v153 op_sel_hi:[0,0,0]
	v_mfma_scale_f32_16x16x128_f8f6f4 v[80:83], v[180:187], v[196:203], v[240:243], v153, v153 op_sel_hi:[0,0,0]
	v_mfma_scale_f32_16x16x128_f8f6f4 v[64:67], v[172:179], v[204:211], v[244:247], v153, v153 op_sel_hi:[0,0,0]
	v_mfma_scale_f32_16x16x128_f8f6f4 v[60:63], v[180:187], v[204:211], v[212:215], v153, v153 op_sel_hi:[0,0,0]
	s_setprio 0
	s_barrier
	ds_read_b128 v[188:191], v152 offset:49152
	ds_read_b128 v[192:195], v152 offset:50176
	ds_read_b128 v[196:199], v152 offset:51200
	ds_read_b128 v[200:203], v152 offset:52224
	ds_read_b128 v[204:207], v152 offset:53248
	ds_read_b128 v[208:211], v152 offset:54272
	ds_read_b128 v[212:215], v152 offset:55296
	ds_read_b128 v[216:219], v152 offset:56320
	s_add_i32 s75, s75, s41
	s_add_u32 s100, s30, s14
	s_addc_u32 s101, s31, s15
	s_mov_b32 m0, s75
	s_add_u32 s30, s36, s49
	global_load_lds_dwordx4 v148, s[100:101]
	s_addc_u32 s31, s37, s50
	s_add_i32 m0, s75, 0x2000
	s_nop 0
	s_add_u32 s100, s30, s14
	s_addc_u32 s101, s31, s15
	s_add_u32 s30, s30, s6
	s_addc_u32 s31, s31, s7
	global_load_lds_dwordx4 v148, s[100:101]
	s_nop 0
	s_add_u32 s100, s30, s14
	s_addc_u32 s101, s31, s15
	s_add_i32 s30, s80, s41
	s_mov_b32 m0, s30
	s_nop 0
	global_load_lds_dwordx4 v148, s[100:101]
	s_add_i32 m0, s30, 0x2000
	s_nop 0
	global_load_lds_dwordx4 v248, s[34:35]
	s_mov_b32 m0, s51
	s_add_u32 s100, s28, s14
	s_addc_u32 s101, s29, s15
	s_add_u32 s28, s38, s49
	s_addc_u32 s29, s39, s50
	global_load_lds_dwordx4 v145, s[100:101]
	s_mov_b32 m0, s21
	s_nop 0
	global_load_lds_dwordx4 v249, s[28:29]
	s_waitcnt vmcnt(8)
	s_waitcnt lgkmcnt(0)
	s_barrier
	s_setprio 1
	s_waitcnt lgkmcnt(0)
	v_mfma_scale_f32_16x16x128_f8f6f4 v[72:75], v[154:161], v[188:195], v[72:75], v153, v153 op_sel_hi:[0,0,0]
	v_mfma_scale_f32_16x16x128_f8f6f4 v[68:71], v[162:169], v[188:195], v[68:71], v153, v153 op_sel_hi:[0,0,0]
	v_mfma_scale_f32_16x16x128_f8f6f4 v[52:55], v[154:161], v[196:203], v[52:55], v153, v153 op_sel_hi:[0,0,0]
	v_mfma_scale_f32_16x16x128_f8f6f4 v[44:47], v[162:169], v[196:203], v[44:47], v153, v153 op_sel_hi:[0,0,0]
	v_mfma_scale_f32_16x16x128_f8f6f4 v[36:39], v[154:161], v[204:211], v[36:39], v153, v153 op_sel_hi:[0,0,0]
	v_mfma_scale_f32_16x16x128_f8f6f4 v[28:31], v[162:169], v[204:211], v[28:31], v153, v153 op_sel_hi:[0,0,0]
	v_mfma_scale_f32_16x16x128_f8f6f4 v[20:23], v[154:161], v[212:219], v[20:23], v153, v153 op_sel_hi:[0,0,0]
	v_mfma_scale_f32_16x16x128_f8f6f4 v[12:15], v[162:169], v[212:219], v[12:15], v153, v153 op_sel_hi:[0,0,0]
	s_setprio 0
	s_setprio 1
	v_mfma_scale_f32_16x16x128_f8f6f4 v[56:59], v[172:179], v[188:195], v[56:59], v153, v153 op_sel_hi:[0,0,0]
	v_mfma_scale_f32_16x16x128_f8f6f4 v[48:51], v[180:187], v[188:195], v[48:51], v153, v153 op_sel_hi:[0,0,0]
	v_mfma_scale_f32_16x16x128_f8f6f4 v[40:43], v[172:179], v[196:203], v[40:43], v153, v153 op_sel_hi:[0,0,0]
	v_mfma_scale_f32_16x16x128_f8f6f4 v[32:35], v[180:187], v[196:203], v[32:35], v153, v153 op_sel_hi:[0,0,0]
	v_mfma_scale_f32_16x16x128_f8f6f4 v[24:27], v[172:179], v[204:211], v[24:27], v153, v153 op_sel_hi:[0,0,0]
	v_mfma_scale_f32_16x16x128_f8f6f4 v[16:19], v[180:187], v[204:211], v[16:19], v153, v153 op_sel_hi:[0,0,0]
	v_mfma_scale_f32_16x16x128_f8f6f4 v[8:11], v[172:179], v[212:219], v[8:11], v153, v153 op_sel_hi:[0,0,0]
	v_mfma_scale_f32_16x16x128_f8f6f4 v[4:7], v[180:187], v[212:219], v[2:5], v153, v153 op_sel_hi:[0,0,0]
	s_setprio 0
	s_barrier
	s_add_u32 s26, s26, 0x100
	s_addc_u32 s27, s27, 0
	s_cmp_ge_i32 s74, s48
	s_cbranch_scc1 .LBB0_421
	s_mov_b32 s28, s74
	s_cmp_lg_u32 s28, 2
	s_cbranch_scc0 .LBB0_418
	s_branch .LBB0_419

; #define PG8_STAGE(bufoff, gbase, voff) do { _Pragma("unroll") for (int _i = 0; _i < 2; ++_i) { unsigned vo_ = (voff)[0]; asm volatile("" : "+v"(vo_));   \
;         __builtin_amdgcn_global_load_lds((const unsigned*)((const char*)(gbase) + (size_t)_i * r64step + vo_), (PG8_LAS unsigned*)(lds + (bufoff) + ldsw + _i * 8192), 16, 0, 0); } } while (0)
; #define PG8_WAIT_V(n) asm volatile("s_waitcnt vmcnt(" #n ")" ::: "memory")
; #define PG8_BAR __builtin_amdgcn_s_barrier()
; template <class Epi, class Sched, bool ALIGN_EPI = false, bool SP2 = false, bool F8 = false>
; __device__ __forceinline__ void gemm_phase(PG8_LAS unsigned char* lds, const Gemm g, const Sched& S, const Epi& E) {
;     ...
;     f32x4 acc[2][2][4][2];
; #pragma unroll
;     for (int a = 0; a < 2; ++a)
; #pragma unroll
;         for (int b = 0; b < 2; ++b)
; #pragma unroll
;             for (int m = 0; m < 4; ++m)
; #pragma unroll
;                 for (int n = 0; n < 2; ++n) acc[a][b][m][n] = (f32x4){0.f, 0.f, 0.f, 0.f};
;     bf16x8 At[4][2], B0[2][2], B1[2][2]; i32x8 At8[4], B08[2], B18[2];
;     const char* cA = (const char*)g.A + (size_t)cur.pm * tstep; const char* cB = (const char*)g.Bt + (size_t)cur.pn * tstep;
;     S.a_ready(cur);
;     if constexpr (SP2) {
;         PG8_STAGE(PG8_SB(0, 0), cB, voffB); PG8_STAGE(PG8_SB(0, 1), cB + hstep, voffB); PG8_STAGE(PG8_SA(0, 0), cA, voffA); PG8_STAGE(PG8_SA(0, 1), cA + hstep, voffA);
;         if (wr == 1) PG8_BAR;
;         PG8_WAIT_V(2); PG8_BAR;
;         PG8_STAGE(PG8_SB(1, 0), cB + kstep, voffB); PG8_STAGE(PG8_SA(1, 0), cA + kstep, voffA); PG8_STAGE(PG8_SB(1, 1), cB + hstep + kstep, voffB);
;         PG8_WAIT_V(6); PG8_BAR;
.LBB0_492:
	v_and_b32_e32 v175, 15, v174
	v_and_b32_e32 v0, 48, v174
	v_lshlrev_b32_e32 v1, 2, v174
	s_and_b32 s39, s47, 3
	s_lshl_b32 s44, s59, 13
	v_lshl_or_b32 v0, v175, 6, v0
	v_and_b32_e32 v1, 32, v1
	v_bitop3_b32 v2, v0, s44, v1 bitop3:0xde
	s_lshl_b32 s44, s39, 12
	v_mov_b32_e32 v148, v128
	v_bitop3_b32 v129, v0, s44, v1 bitop3:0xde
	s_waitcnt vmcnt(2)
	s_barrier
	s_add_i32 m0, s61, 0x18000
	v_lshl_add_u64 v[0:1], s[0:1], 0, v[148:149]
	v_lshl_add_u64 v[0:1], v[0:1], 0, s[20:21]
	v_mov_b32_e32 v148, v128
	global_load_lds_dwordx4 v[0:1], off
	s_add_i32 m0, s61, 0x1a000
	v_lshl_add_u64 v[0:1], s[0:1], 0, v[148:149]
	v_lshl_add_u64 v[0:1], v[0:1], 0, s[22:23]
	v_mov_b32_e32 v148, v128
	global_load_lds_dwordx4 v[0:1], off
	s_add_i32 s65, s61, 0x8000
	v_lshl_add_u64 v[0:1], s[6:7], 0, v[148:149]
	v_lshl_add_u64 v[0:1], v[0:1], 0, s[20:21]
	s_mov_b32 m0, s65
	v_mov_b32_e32 v148, v128
	global_load_lds_dwordx4 v[0:1], off
	s_add_i32 s66, s61, 0xa000
	v_lshl_add_u64 v[0:1], s[6:7], 0, v[148:149]
	v_lshl_add_u64 v[0:1], v[0:1], 0, s[22:23]
	s_mov_b32 m0, s66
	v_mov_b32_e32 v148, v128
	global_load_lds_dwordx4 v[0:1], off
	s_add_i32 m0, s61, 0x1c000
	v_lshl_add_u64 v[0:1], s[0:1], 0, v[148:149]
	v_lshl_add_u64 v[0:1], v[0:1], 0, s[24:25]
	v_mov_b32_e32 v148, v128
	global_load_lds_dwordx4 v[0:1], off
	s_add_i32 m0, s61, 0x1e000
	v_lshl_add_u64 v[0:1], s[0:1], 0, v[148:149]
	v_lshl_add_u64 v[0:1], v[0:1], 0, s[26:27]
	global_load_lds_dwordx4 v[0:1], off
	s_add_u32 s67, s96, s40
	s_waitcnt vmcnt(6)
	s_addc_u32 s68, s97, s41
	s_add_u32 s69, s49, s42
	v_mov_b32_e32 v104, 0
	v_lshl_or_b32 v153, s59, 6, v175
	s_addc_u32 s70, s50, s43
	s_mov_b32 s71, -2
	s_mov_b64 s[40:41], 0
	v_add_u32_e32 v130, 0, v2
	v_mov_b32_e32 v105, v104
	v_mov_b32_e32 v106, v104
	v_mov_b32_e32 v107, v104
	v_mov_b32_e32 v0, v104
	v_mov_b32_e32 v1, v104
	v_mov_b32_e32 v2, v104
	v_mov_b32_e32 v3, v104
	v_mov_b32_e32 v112, v104
	v_mov_b32_e32 v113, v104
	v_mov_b32_e32 v114, v104
	v_mov_b32_e32 v115, v104
	v_mov_b32_e32 v12, v104
	v_mov_b32_e32 v13, v104
	v_mov_b32_e32 v14, v104
	v_mov_b32_e32 v15, v104
	v_mov_b32_e32 v120, v104
	v_mov_b32_e32 v121, v104
	v_mov_b32_e32 v122, v104
	v_mov_b32_e32 v123, v104
	v_mov_b32_e32 v36, v104
	v_mov_b32_e32 v37, v104
	v_mov_b32_e32 v38, v104
	v_mov_b32_e32 v39, v104
	v_mov_b32_e32 v124, v104
	v_mov_b32_e32 v125, v104
	v_mov_b32_e32 v126, v104
	v_mov_b32_e32 v127, v104
	v_mov_b32_e32 v56, v104
	v_mov_b32_e32 v57, v104
	v_mov_b32_e32 v58, v104
	v_mov_b32_e32 v59, v104
	v_mov_b32_e32 v8, v104
	v_mov_b32_e32 v9, v104
	v_mov_b32_e32 v10, v104
	v_mov_b32_e32 v11, v104
	v_mov_b32_e32 v28, v104
	v_mov_b32_e32 v29, v104
	v_mov_b32_e32 v30, v104
	v_mov_b32_e32 v31, v104
	v_mov_b32_e32 v24, v104
	v_mov_b32_e32 v25, v104
	v_mov_b32_e32 v26, v104
	v_mov_b32_e32 v27, v104
	v_mov_b32_e32 v44, v104
	v_mov_b32_e32 v45, v104
	v_mov_b32_e32 v46, v104
	v_mov_b32_e32 v47, v104
	v_mov_b32_e32 v48, v104
	v_mov_b32_e32 v49, v104
	v_mov_b32_e32 v50, v104
	v_mov_b32_e32 v51, v104
	v_mov_b32_e32 v88, v104
	v_mov_b32_e32 v89, v104
	v_mov_b32_e32 v90, v104
	v_mov_b32_e32 v91, v104
	v_mov_b32_e32 v68, v104
	v_mov_b32_e32 v69, v104
	v_mov_b32_e32 v70, v104
	v_mov_b32_e32 v71, v104
	v_mov_b32_e32 v92, v104
	v_mov_b32_e32 v93, v104
	v_mov_b32_e32 v94, v104
	v_mov_b32_e32 v95, v104
	v_mov_b32_e32 v96, v104
	v_mov_b32_e32 v97, v104
	v_mov_b32_e32 v98, v104
	v_mov_b32_e32 v99, v104
	v_mov_b32_e32 v4, v104
	v_mov_b32_e32 v5, v104
	v_mov_b32_e32 v6, v104
	v_mov_b32_e32 v7, v104
	v_mov_b32_e32 v100, v104
	v_mov_b32_e32 v101, v104
	v_mov_b32_e32 v102, v104
	v_mov_b32_e32 v103, v104
	v_mov_b32_e32 v20, v104
	v_mov_b32_e32 v21, v104
	v_mov_b32_e32 v22, v104
	v_mov_b32_e32 v23, v104
	v_mov_b32_e32 v108, v104
	v_mov_b32_e32 v109, v104
	v_mov_b32_e32 v110, v104
	v_mov_b32_e32 v111, v104
	v_mov_b32_e32 v40, v104
	v_mov_b32_e32 v41, v104
	v_mov_b32_e32 v42, v104
	v_mov_b32_e32 v43, v104
	v_mov_b32_e32 v116, v104
	v_mov_b32_e32 v117, v104
	v_mov_b32_e32 v118, v104
	v_mov_b32_e32 v119, v104
	v_mov_b32_e32 v72, v104
	v_mov_b32_e32 v73, v104
	v_mov_b32_e32 v74, v104
	v_mov_b32_e32 v75, v104
	v_mov_b32_e32 v16, v104
	v_mov_b32_e32 v17, v104
	v_mov_b32_e32 v18, v104
	v_mov_b32_e32 v19, v104
	v_mov_b32_e32 v60, v104
	v_mov_b32_e32 v61, v104
	v_mov_b32_e32 v62, v104
	v_mov_b32_e32 v63, v104
	v_mov_b32_e32 v32, v104
	v_mov_b32_e32 v33, v104
	v_mov_b32_e32 v34, v104
	v_mov_b32_e32 v35, v104
	v_mov_b32_e32 v64, v104
	v_mov_b32_e32 v65, v104
	v_mov_b32_e32 v66, v104
	v_mov_b32_e32 v67, v104
	v_mov_b32_e32 v52, v104
	v_mov_b32_e32 v53, v104
	v_mov_b32_e32 v54, v104
	v_mov_b32_e32 v55, v104
	v_mov_b32_e32 v76, v104
	v_mov_b32_e32 v77, v104
	v_mov_b32_e32 v78, v104
	v_mov_b32_e32 v79, v104
	v_mov_b32_e32 v84, v104
	v_mov_b32_e32 v85, v104
	v_mov_b32_e32 v86, v104
	v_mov_b32_e32 v87, v104
	v_mov_b32_e32 v80, v104
	v_mov_b32_e32 v81, v104
	v_mov_b32_e32 v82, v104
	v_mov_b32_e32 v83, v104
	s_barrier
	v_add_u32_e32 v216, s28, v128
	v_add_u32_e32 v217, s30, v128
	v_add_u32_e32 v218, s14, v128
	v_add_u32_e32 v219, s16, v128
	v_add_u32_e32 v220, s18, v128
	v_add_u32_e32 v221, s20, v128
	v_add_u32_e32 v222, s22, v128
	v_add_u32_e32 v223, s24, v128
	v_add_u32_e32 v224, s26, v128
; #define PG8_STAGE(bufoff, gbase, voff) do { _Pragma("unroll") for (int _i = 0; _i < 2; ++_i) { unsigned vo_ = (voff)[0]; asm volatile("" : "+v"(vo_));   \
;         __builtin_amdgcn_global_load_lds((const unsigned*)((const char*)(gbase) + (size_t)_i * r64step + vo_), (PG8_LAS unsigned*)(lds + (bufoff) + ldsw + _i * 8192), 16, 0, 0); } } while (0)
; #define PG8_WAIT_V(n) asm volatile("s_waitcnt vmcnt(" #n ")" ::: "memory")
; #define PG8_WAIT_L(n) asm volatile("s_waitcnt lgkmcnt(" #n ")" ::: "memory")
; #define PG8_BAR __builtin_amdgcn_s_barrier()
; #define PG8_SCHED __builtin_amdgcn_sched_barrier(0)
; template <class Epi, class Sched, bool ALIGN_EPI = false, bool SP2 = false, bool F8 = false>
; __device__ __forceinline__ void gemm_phase(PG8_LAS unsigned char* lds, const Gemm g, const Sched& S, const Epi& E) {
;     ...
;             PG8_LDB(B0, 0, 0); PG8_LDB(B1, 0, 1); PG8_SCHED; PG8_LDA(At, 0, 0); PG8_STAGE(PG8_SA(1, 1), a1 + hstep, voffA);
;             PG8_WAIT_V(8); PG8_WAIT_L(0); PG8_BAR; PG8_MMA(0, 0, At, B0); PG8_MMA(0, 1, At, B1); PG8_BAR; PG8_SCHED;
;             PG8_LDA(At, 0, 1); PG8_STAGE(PG8_SB(0, 0), b2, voffB); PG8_STAGE(PG8_SB(0, 1), b2 + hstep, voffB); PG8_STAGE(PG8_SA(0, 0), a2, voffA);
;             PG8_WAIT_V(8); PG8_WAIT_L(0); PG8_BAR; PG8_MMA(1, 0, At, B0); PG8_MMA(1, 1, At, B1); PG8_BAR; PG8_SCHED;
.LBB0_493:
	s_add_u32 s72, s67, s40
	s_addc_u32 s73, s68, s41
	s_add_u32 s42, s72, 0x10000100
	s_addc_u32 s43, s73, 0
	s_add_u32 s44, s69, s40
	s_addc_u32 s45, s70, s41
	s_add_i32 s74, 0, 0x10000
	s_cmpk_eq_i32 s40, 0x700
	s_cselect_b32 s43, s7, s43
	s_cselect_b32 s42, s6, s42
	v_add_u32_e32 v131, s74, v129
	s_cselect_b32 s45, s1, s45
	s_cselect_b32 s44, s0, s44
	s_add_i32 s75, 0, 0x14000
	ds_read_b128 v[132:135], v131
	ds_read_b128 v[136:139], v131 offset:1024
	ds_read_b128 v[140:143], v131 offset:2048
	ds_read_b128 v[154:157], v131 offset:3072
	v_add_u32_e32 v131, s75, v129
	ds_read_b128 v[158:161], v131
	ds_read_b128 v[162:165], v131 offset:1024
	ds_read_b128 v[176:179], v131 offset:2048
	ds_read_b128 v[180:183], v131 offset:3072
	ds_read_b128 v[184:187], v130
	ds_read_b128 v[188:191], v130 offset:1024
	ds_read_b128 v[192:195], v130 offset:2048
	ds_read_b128 v[196:199], v130 offset:3072
	ds_read_b128 v[200:203], v130 offset:4096
	ds_read_b128 v[204:207], v130 offset:5120
	ds_read_b128 v[208:211], v130 offset:6144
	ds_read_b128 v[212:215], v130 offset:7168
	s_add_i32 m0, s61, 0xc000
	s_nop 0
	global_load_lds_dwordx4 v216, s[72:73]
	s_add_i32 m0, s61, 0xe000
	s_nop 0
	global_load_lds_dwordx4 v217, s[72:73]
	s_waitcnt vmcnt(8)
	s_waitcnt lgkmcnt(0)
	s_barrier
	s_setprio 1
	s_waitcnt lgkmcnt(0)
	v_mfma_f32_16x16x32_bf16 v[80:83], v[132:135], v[184:187], v[80:83]
	v_mfma_f32_16x16x32_bf16 v[84:87], v[140:143], v[184:187], v[84:87]
	v_mfma_f32_16x16x32_bf16 v[76:79], v[132:135], v[192:195], v[76:79]
	v_mfma_f32_16x16x32_bf16 v[52:55], v[140:143], v[192:195], v[52:55]
	v_mfma_f32_16x16x32_bf16 v[64:67], v[132:135], v[200:203], v[64:67]
	v_mfma_f32_16x16x32_bf16 v[32:35], v[140:143], v[200:203], v[32:35]
	v_mfma_f32_16x16x32_bf16 v[60:63], v[132:135], v[208:211], v[60:63]
	v_mfma_f32_16x16x32_bf16 v[16:19], v[140:143], v[208:211], v[16:19]
	v_mfma_f32_16x16x32_bf16 v[80:83], v[136:139], v[188:191], v[80:83]
	v_mfma_f32_16x16x32_bf16 v[84:87], v[154:157], v[188:191], v[84:87]
	v_mfma_f32_16x16x32_bf16 v[76:79], v[136:139], v[196:199], v[76:79]
	v_mfma_f32_16x16x32_bf16 v[52:55], v[154:157], v[196:199], v[52:55]
	v_mfma_f32_16x16x32_bf16 v[64:67], v[136:139], v[204:207], v[64:67]
	v_mfma_f32_16x16x32_bf16 v[32:35], v[154:157], v[204:207], v[32:35]
	v_mfma_f32_16x16x32_bf16 v[60:63], v[136:139], v[212:215], v[60:63]
	v_mfma_f32_16x16x32_bf16 v[16:19], v[154:157], v[212:215], v[16:19]
	s_setprio 0
	s_setprio 1
	v_mfma_f32_16x16x32_bf16 v[72:75], v[158:161], v[184:187], v[72:75]
	v_mfma_f32_16x16x32_bf16 v[116:119], v[176:179], v[184:187], v[116:119]
	v_mfma_f32_16x16x32_bf16 v[40:43], v[158:161], v[192:195], v[40:43]
	v_mfma_f32_16x16x32_bf16 v[108:111], v[176:179], v[192:195], v[108:111]
	v_mfma_f32_16x16x32_bf16 v[20:23], v[158:161], v[200:203], v[20:23]
	v_mfma_f32_16x16x32_bf16 v[100:103], v[176:179], v[200:203], v[100:103]
	v_mfma_f32_16x16x32_bf16 v[4:7], v[158:161], v[208:211], v[4:7]
	v_mfma_f32_16x16x32_bf16 v[96:99], v[176:179], v[208:211], v[96:99]
	v_mfma_f32_16x16x32_bf16 v[72:75], v[162:165], v[188:191], v[72:75]
	v_mfma_f32_16x16x32_bf16 v[116:119], v[180:183], v[188:191], v[116:119]
	v_mfma_f32_16x16x32_bf16 v[40:43], v[162:165], v[196:199], v[40:43]
	v_mfma_f32_16x16x32_bf16 v[108:111], v[180:183], v[196:199], v[108:111]
	v_mfma_f32_16x16x32_bf16 v[20:23], v[162:165], v[204:207], v[20:23]
	v_mfma_f32_16x16x32_bf16 v[100:103], v[180:183], v[204:207], v[100:103]
	v_mfma_f32_16x16x32_bf16 v[4:7], v[162:165], v[212:215], v[4:7]
	v_mfma_f32_16x16x32_bf16 v[96:99], v[180:183], v[212:215], v[96:99]
	s_setprio 0
	s_barrier
	s_add_i32 s72, s74, s60
	s_mov_b32 m0, s72
	ds_read_b128 v[184:187], v130 offset:16384
	ds_read_b128 v[188:191], v130 offset:17408
	ds_read_b128 v[192:195], v130 offset:18432
	ds_read_b128 v[196:199], v130 offset:19456
	ds_read_b128 v[200:203], v130 offset:20480
	ds_read_b128 v[204:207], v130 offset:21504
	ds_read_b128 v[208:211], v130 offset:22528
	ds_read_b128 v[212:215], v130 offset:23552
	s_nop 0
	global_load_lds_dwordx4 v128, s[44:45]
	s_add_i32 m0, s72, 0x2000
	s_nop 0
	global_load_lds_dwordx4 v218, s[44:45]
	s_add_i32 s72, s75, s60
	s_mov_b32 m0, s72
	s_nop 0
	global_load_lds_dwordx4 v219, s[44:45]
	s_add_i32 m0, s72, 0x2000
	s_nop 0
	global_load_lds_dwordx4 v220, s[44:45]
	s_mov_b32 m0, s61
	s_nop 0
	global_load_lds_dwordx4 v128, s[42:43]
	s_mov_b32 m0, s62
	s_nop 0
	global_load_lds_dwordx4 v218, s[42:43]
	s_waitcnt vmcnt(8)
	s_waitcnt lgkmcnt(0)
	s_barrier
	s_setprio 1
	s_waitcnt lgkmcnt(0)
	v_mfma_f32_16x16x32_bf16 v[92:95], v[132:135], v[184:187], v[92:95]
	v_mfma_f32_16x16x32_bf16 v[68:71], v[140:143], v[184:187], v[68:71]
	v_mfma_f32_16x16x32_bf16 v[88:91], v[132:135], v[192:195], v[88:91]
	v_mfma_f32_16x16x32_bf16 v[48:51], v[140:143], v[192:195], v[48:51]
	v_mfma_f32_16x16x32_bf16 v[44:47], v[132:135], v[200:203], v[44:47]
	v_mfma_f32_16x16x32_bf16 v[24:27], v[140:143], v[200:203], v[24:27]
	v_mfma_f32_16x16x32_bf16 v[28:31], v[132:135], v[208:211], v[28:31]
	v_mfma_f32_16x16x32_bf16 v[8:11], v[140:143], v[208:211], v[8:11]
	v_mfma_f32_16x16x32_bf16 v[92:95], v[136:139], v[188:191], v[92:95]
	v_mfma_f32_16x16x32_bf16 v[68:71], v[154:157], v[188:191], v[68:71]
	v_mfma_f32_16x16x32_bf16 v[88:91], v[136:139], v[196:199], v[88:91]
	v_mfma_f32_16x16x32_bf16 v[48:51], v[154:157], v[196:199], v[48:51]
	v_mfma_f32_16x16x32_bf16 v[44:47], v[136:139], v[204:207], v[44:47]
	v_mfma_f32_16x16x32_bf16 v[24:27], v[154:157], v[204:207], v[24:27]
	v_mfma_f32_16x16x32_bf16 v[28:31], v[136:139], v[212:215], v[28:31]
	v_mfma_f32_16x16x32_bf16 v[8:11], v[154:157], v[212:215], v[8:11]
	s_setprio 0
	s_setprio 1
	v_mfma_f32_16x16x32_bf16 v[56:59], v[158:161], v[184:187], v[56:59]
	v_mfma_f32_16x16x32_bf16 v[124:127], v[176:179], v[184:187], v[124:127]
	v_mfma_f32_16x16x32_bf16 v[36:39], v[158:161], v[192:195], v[36:39]
	v_mfma_f32_16x16x32_bf16 v[120:123], v[176:179], v[192:195], v[120:123]
	v_mfma_f32_16x16x32_bf16 v[12:15], v[158:161], v[200:203], v[12:15]
	v_mfma_f32_16x16x32_bf16 v[112:115], v[176:179], v[200:203], v[112:115]
	v_mfma_f32_16x16x32_bf16 v[0:3], v[158:161], v[208:211], v[0:3]
	v_mfma_f32_16x16x32_bf16 v[104:107], v[176:179], v[208:211], v[104:107]
	v_mfma_f32_16x16x32_bf16 v[56:59], v[162:165], v[188:191], v[56:59]
	v_mfma_f32_16x16x32_bf16 v[124:127], v[180:183], v[188:191], v[124:127]
	v_mfma_f32_16x16x32_bf16 v[36:39], v[162:165], v[196:199], v[36:39]
	v_mfma_f32_16x16x32_bf16 v[120:123], v[180:183], v[196:199], v[120:123]
	v_mfma_f32_16x16x32_bf16 v[12:15], v[162:165], v[204:207], v[12:15]
	v_mfma_f32_16x16x32_bf16 v[112:115], v[180:183], v[204:207], v[112:115]
	v_mfma_f32_16x16x32_bf16 v[0:3], v[162:165], v[212:215], v[0:3]
	v_mfma_f32_16x16x32_bf16 v[104:107], v[180:183], v[212:215], v[104:107]
	s_setprio 0
	s_barrier
; #define PG8_STAGE(bufoff, gbase, voff) do { _Pragma("unroll") for (int _i = 0; _i < 2; ++_i) { unsigned vo_ = (voff)[0]; asm volatile("" : "+v"(vo_));   \
;         __builtin_amdgcn_global_load_lds((const unsigned*)((const char*)(gbase) + (size_t)_i * r64step + vo_), (PG8_LAS unsigned*)(lds + (bufoff) + ldsw + _i * 8192), 16, 0, 0); } } while (0)
; #define PG8_WAIT_V(n) asm volatile("s_waitcnt vmcnt(" #n ")" ::: "memory")
; #define PG8_WAIT_L(n) asm volatile("s_waitcnt lgkmcnt(" #n ")" ::: "memory")
; #define PG8_BAR __builtin_amdgcn_s_barrier()
; #define PG8_SCHED __builtin_amdgcn_sched_barrier(0)
; template <class Epi, class Sched, bool ALIGN_EPI = false, bool SP2 = false, bool F8 = false>
; __device__ __forceinline__ void gemm_phase(PG8_LAS unsigned char* lds, const Gemm g, const Sched& S, const Epi& E) {
;     ...
;             PG8_LDB(B0, 1, 0); PG8_LDB(B1, 1, 1); PG8_SCHED; PG8_LDA(At, 1, 0); PG8_STAGE(PG8_SA(0, 1), a2 + hstep, voffA);
;             PG8_WAIT_V(8); PG8_WAIT_L(0); PG8_BAR; PG8_MMA(0, 0, At, B0); PG8_MMA(0, 1, At, B1); PG8_BAR; PG8_SCHED;
;             PG8_LDA(At, 1, 1); PG8_STAGE(PG8_SB(1, 0), b3, voffB); PG8_STAGE(PG8_SB(1, 1), b3 + hstep, voffB); PG8_STAGE(PG8_SA(1, 0), a3, voffA);
;             PG8_WAIT_V(8); PG8_WAIT_L(0); PG8_BAR; PG8_MMA(1, 0, At, B0); PG8_MMA(1, 1, At, B1); PG8_BAR; PG8_SCHED;
;     ...
;     PG8_WAIT_V(0);
;     if constexpr (!ALIGN_EPI) { if (wr == 0) PG8_BAR; }
	s_add_i32 s72, 0, 0x18000
	v_add_u32_e32 v131, s72, v129
	s_add_i32 s73, 0, 0x1c000
	ds_read_b128 v[132:135], v131
	ds_read_b128 v[136:139], v131 offset:1024
	ds_read_b128 v[140:143], v131 offset:2048
	ds_read_b128 v[154:157], v131 offset:3072
	v_add_u32_e32 v131, s73, v129
	ds_read_b128 v[158:161], v131
	ds_read_b128 v[162:165], v131 offset:1024
	ds_read_b128 v[176:179], v131 offset:2048
	ds_read_b128 v[180:183], v131 offset:3072
	ds_read_b128 v[184:187], v130 offset:32768
	ds_read_b128 v[188:191], v130 offset:33792
	ds_read_b128 v[192:195], v130 offset:34816
	ds_read_b128 v[196:199], v130 offset:35840
	ds_read_b128 v[200:203], v130 offset:36864
	ds_read_b128 v[204:207], v130 offset:37888
	ds_read_b128 v[208:211], v130 offset:38912
	ds_read_b128 v[212:215], v130 offset:39936
	s_mov_b32 m0, s63
	s_nop 0
	global_load_lds_dwordx4 v219, s[42:43]
	s_mov_b32 m0, s64
	s_nop 0
	global_load_lds_dwordx4 v220, s[42:43]
	s_waitcnt vmcnt(8)
	s_waitcnt lgkmcnt(0)
	s_barrier
	s_setprio 1
	s_waitcnt lgkmcnt(0)
	v_mfma_f32_16x16x32_bf16 v[80:83], v[132:135], v[184:187], v[80:83]
	v_mfma_f32_16x16x32_bf16 v[84:87], v[140:143], v[184:187], v[84:87]
	v_mfma_f32_16x16x32_bf16 v[76:79], v[132:135], v[192:195], v[76:79]
	v_mfma_f32_16x16x32_bf16 v[52:55], v[140:143], v[192:195], v[52:55]
	v_mfma_f32_16x16x32_bf16 v[64:67], v[132:135], v[200:203], v[64:67]
	v_mfma_f32_16x16x32_bf16 v[32:35], v[140:143], v[200:203], v[32:35]
	v_mfma_f32_16x16x32_bf16 v[60:63], v[132:135], v[208:211], v[60:63]
	v_mfma_f32_16x16x32_bf16 v[16:19], v[140:143], v[208:211], v[16:19]
	v_mfma_f32_16x16x32_bf16 v[80:83], v[136:139], v[188:191], v[80:83]
	v_mfma_f32_16x16x32_bf16 v[84:87], v[154:157], v[188:191], v[84:87]
	v_mfma_f32_16x16x32_bf16 v[76:79], v[136:139], v[196:199], v[76:79]
	v_mfma_f32_16x16x32_bf16 v[52:55], v[154:157], v[196:199], v[52:55]
	v_mfma_f32_16x16x32_bf16 v[64:67], v[136:139], v[204:207], v[64:67]
	v_mfma_f32_16x16x32_bf16 v[32:35], v[154:157], v[204:207], v[32:35]
	v_mfma_f32_16x16x32_bf16 v[60:63], v[136:139], v[212:215], v[60:63]
	v_mfma_f32_16x16x32_bf16 v[16:19], v[154:157], v[212:215], v[16:19]
	s_setprio 0
	s_setprio 1
	v_mfma_f32_16x16x32_bf16 v[72:75], v[158:161], v[184:187], v[72:75]
	v_mfma_f32_16x16x32_bf16 v[116:119], v[176:179], v[184:187], v[116:119]
	v_mfma_f32_16x16x32_bf16 v[40:43], v[158:161], v[192:195], v[40:43]
	v_mfma_f32_16x16x32_bf16 v[108:111], v[176:179], v[192:195], v[108:111]
	v_mfma_f32_16x16x32_bf16 v[20:23], v[158:161], v[200:203], v[20:23]
	v_mfma_f32_16x16x32_bf16 v[100:103], v[176:179], v[200:203], v[100:103]
	v_mfma_f32_16x16x32_bf16 v[4:7], v[158:161], v[208:211], v[4:7]
	v_mfma_f32_16x16x32_bf16 v[96:99], v[176:179], v[208:211], v[96:99]
	v_mfma_f32_16x16x32_bf16 v[72:75], v[162:165], v[188:191], v[72:75]
	v_mfma_f32_16x16x32_bf16 v[116:119], v[180:183], v[188:191], v[116:119]
	v_mfma_f32_16x16x32_bf16 v[40:43], v[162:165], v[196:199], v[40:43]
	v_mfma_f32_16x16x32_bf16 v[108:111], v[180:183], v[196:199], v[108:111]
	v_mfma_f32_16x16x32_bf16 v[20:23], v[162:165], v[204:207], v[20:23]
	v_mfma_f32_16x16x32_bf16 v[100:103], v[180:183], v[204:207], v[100:103]
	v_mfma_f32_16x16x32_bf16 v[4:7], v[162:165], v[212:215], v[4:7]
	v_mfma_f32_16x16x32_bf16 v[96:99], v[180:183], v[212:215], v[96:99]
	s_setprio 0
	s_barrier
	ds_read_b128 v[184:187], v130 offset:49152
	ds_read_b128 v[188:191], v130 offset:50176
	ds_read_b128 v[192:195], v130 offset:51200
	ds_read_b128 v[196:199], v130 offset:52224
	ds_read_b128 v[200:203], v130 offset:53248
	ds_read_b128 v[204:207], v130 offset:54272
	ds_read_b128 v[208:211], v130 offset:55296
	ds_read_b128 v[212:215], v130 offset:56320
	s_add_i32 s72, s72, s60
	s_mov_b32 m0, s72
	s_nop 0
	global_load_lds_dwordx4 v221, s[44:45]
	s_add_i32 m0, s72, 0x2000
	s_nop 0
	global_load_lds_dwordx4 v222, s[44:45]
	s_add_i32 s72, s73, s60
	s_mov_b32 m0, s72
	s_nop 0
	global_load_lds_dwordx4 v223, s[44:45]
	s_add_i32 m0, s72, 0x2000
	s_nop 0
	global_load_lds_dwordx4 v224, s[44:45]
	s_mov_b32 m0, s65
	s_nop 0
	global_load_lds_dwordx4 v221, s[42:43]
	s_mov_b32 m0, s66
	s_nop 0
	global_load_lds_dwordx4 v222, s[42:43]
	s_waitcnt vmcnt(8)
	s_waitcnt lgkmcnt(0)
	s_barrier
	s_setprio 1
	s_waitcnt lgkmcnt(0)
	v_mfma_f32_16x16x32_bf16 v[92:95], v[132:135], v[184:187], v[92:95]
	v_mfma_f32_16x16x32_bf16 v[68:71], v[140:143], v[184:187], v[68:71]
	v_mfma_f32_16x16x32_bf16 v[88:91], v[132:135], v[192:195], v[88:91]
	v_mfma_f32_16x16x32_bf16 v[48:51], v[140:143], v[192:195], v[48:51]
	v_mfma_f32_16x16x32_bf16 v[44:47], v[132:135], v[200:203], v[44:47]
	v_mfma_f32_16x16x32_bf16 v[24:27], v[140:143], v[200:203], v[24:27]
	v_mfma_f32_16x16x32_bf16 v[28:31], v[132:135], v[208:211], v[28:31]
	v_mfma_f32_16x16x32_bf16 v[8:11], v[140:143], v[208:211], v[8:11]
	v_mfma_f32_16x16x32_bf16 v[92:95], v[136:139], v[188:191], v[92:95]
	v_mfma_f32_16x16x32_bf16 v[68:71], v[154:157], v[188:191], v[68:71]
	v_mfma_f32_16x16x32_bf16 v[88:91], v[136:139], v[196:199], v[88:91]
	v_mfma_f32_16x16x32_bf16 v[48:51], v[154:157], v[196:199], v[48:51]
	v_mfma_f32_16x16x32_bf16 v[44:47], v[136:139], v[204:207], v[44:47]
	v_mfma_f32_16x16x32_bf16 v[24:27], v[154:157], v[204:207], v[24:27]
	v_mfma_f32_16x16x32_bf16 v[28:31], v[136:139], v[212:215], v[28:31]
	v_mfma_f32_16x16x32_bf16 v[8:11], v[154:157], v[212:215], v[8:11]
	s_setprio 0
	s_setprio 1
	v_mfma_f32_16x16x32_bf16 v[56:59], v[158:161], v[184:187], v[56:59]
	v_mfma_f32_16x16x32_bf16 v[124:127], v[176:179], v[184:187], v[124:127]
	v_mfma_f32_16x16x32_bf16 v[36:39], v[158:161], v[192:195], v[36:39]
	v_mfma_f32_16x16x32_bf16 v[120:123], v[176:179], v[192:195], v[120:123]
	v_mfma_f32_16x16x32_bf16 v[12:15], v[158:161], v[200:203], v[12:15]
	v_mfma_f32_16x16x32_bf16 v[112:115], v[176:179], v[200:203], v[112:115]
	v_mfma_f32_16x16x32_bf16 v[0:3], v[158:161], v[208:211], v[0:3]
	v_mfma_f32_16x16x32_bf16 v[104:107], v[176:179], v[208:211], v[104:107]
	v_mfma_f32_16x16x32_bf16 v[56:59], v[162:165], v[188:191], v[56:59]
	v_mfma_f32_16x16x32_bf16 v[124:127], v[180:183], v[188:191], v[124:127]
	v_mfma_f32_16x16x32_bf16 v[36:39], v[162:165], v[196:199], v[36:39]
	v_mfma_f32_16x16x32_bf16 v[120:123], v[180:183], v[196:199], v[120:123]
	v_mfma_f32_16x16x32_bf16 v[12:15], v[162:165], v[204:207], v[12:15]
	v_mfma_f32_16x16x32_bf16 v[112:115], v[180:183], v[204:207], v[112:115]
	v_mfma_f32_16x16x32_bf16 v[0:3], v[162:165], v[212:215], v[0:3]
	v_mfma_f32_16x16x32_bf16 v[104:107], v[180:183], v[212:215], v[104:107]
	s_setprio 0
	s_barrier
	s_add_i32 s71, s71, 2
	s_add_u32 s40, s40, 0x100
	s_addc_u32 s41, s41, 0
	s_cmp_lt_u32 s71, 14
	s_cbranch_scc1 .LBB0_493
	s_waitcnt vmcnt(0)
	s_cmpk_gt_u32 s46, 0xff
	s_cbranch_scc1 .LBB0_496
	s_barrier
